# hand-written DOWN epilogue (batched loads before stores) applying LayerNorm1 on the fly from per-row stats; LN1 phase no longer writes its f32 output
# baseline (speedup 1.0000x reference)
; __device__ __forceinline__ int otid(int wv0) { int t = (wv0 << 6) | olane(); asm volatile("" : "+v"(t)); return t; }
; __device__ __forceinline__ int obid() { int b = blockIdx.x; asm volatile("" : "+s"(b)); return b; }
; __device__ __forceinline__ int ogrid() { int g = gridDim.x; asm volatile("" : "+s"(g)); return g; }
; __device__ __forceinline__ void ln_phase(const float* in, float* outf, bf16_t* outb, const float* g, const float* b, int wv0) {
;   const int tid_ = otid(wv0); const int lane = tid_ & 63, wv = obid() * 8 + (tid_ >> 6), nwv = ogrid() * 8;
;   f32x4 gg[8], bb[8];
; #pragma unroll
;   for (int i = 0; i < 8; ++i) { gg[i] = ((const f32x4*)g)[i * 64 + lane]; bb[i] = ((const f32x4*)b)[i * 64 + lane]; }
;   f32x4 vn[8];
;   if (wv < NTOK) { const f32x4* ir = (const f32x4*)(in + (size_t)wv * DM);
; #pragma unroll
;     for (int i = 0; i < 8; ++i) vn[i] = ir[i * 64 + lane]; }
.LBB0_1158:
	s_or_b64 exec, exec, s[2:3]
	s_waitcnt lgkmcnt(0)
	s_barrier
	s_mov_b32 s0, -1
	s_load_dwordx2 s[4:5], s[54:55], 0xd0
	s_lshl_b32 s1, s53, 6
	v_mbcnt_lo_u32_b32 v0, s0, 0
	v_mbcnt_hi_u32_b32 v0, s0, v0
	v_or_b32_e32 v0, s1, v0
	s_mov_b32 s2, s82
	v_ashrrev_i32_e32 v1, 6, v0
	s_mov_b32 s0, s60
	v_lshl_add_u32 v130, s2, 3, v1
	v_cmp_gt_i32_e32 vcc, s61, v130
	s_and_saveexec_b64 s[6:7], vcc
	s_cbranch_execz .LBB0_1163
	s_load_dwordx4 s[8:11], s[54:55], 0x88
	s_lshl_b32 s2, s66, 11
	s_ashr_i32 s3, s2, 31
	s_lshl_b64 s[2:3], s[2:3], 2
	s_waitcnt vmcnt(8)
	v_and_b32_e32 v78, 63, v0
	s_waitcnt lgkmcnt(0)
	s_add_u32 s100, s4, 0x27700000
	s_addc_u32 s101, s5, 0
	s_add_u32 s8, s8, s2
	s_addc_u32 s9, s9, s3
	s_add_u32 s2, s10, s2
	v_lshlrev_b32_e32 v96, 4, v78
	s_addc_u32 s3, s11, s3
	global_load_dwordx4 v[0:3], v96, s[8:9]
	global_load_dwordx4 v[4:7], v96, s[8:9] offset:1024
	global_load_dwordx4 v[8:11], v96, s[2:3]
	global_load_dwordx4 v[12:15], v96, s[2:3] offset:1024
	global_load_dwordx4 v[16:19], v96, s[8:9] offset:2048
	global_load_dwordx4 v[20:23], v96, s[8:9] offset:3072
	global_load_dwordx4 v[24:27], v96, s[2:3] offset:2048
	global_load_dwordx4 v[28:31], v96, s[2:3] offset:3072
	v_ashrrev_i32_e32 v131, 31, v130
	v_lshlrev_b64 v[132:133], 13, v[130:131]
	v_lshl_add_u64 v[64:65], s[4:5], 0, v[132:133]
	s_mov_b64 s[10:11], 0x8900000
	v_or_b32_e32 v56, 0x1000, v96
	v_mov_b32_e32 v57, v97
	v_or_b32_e32 v58, 0x1400, v96
	v_mov_b32_e32 v59, v97
	v_or_b32_e32 v60, 0x1800, v96
	v_mov_b32_e32 v61, v97
	v_or_b32_e32 v62, 0x1c00, v96
	v_mov_b32_e32 v63, v97
	v_lshl_add_u64 v[64:65], v[64:65], 0, s[10:11]
	global_load_dwordx4 v[32:35], v56, s[8:9]
	global_load_dwordx4 v[36:39], v56, s[2:3]
	global_load_dwordx4 v[40:43], v58, s[8:9]
	global_load_dwordx4 v[44:47], v58, s[2:3]
	global_load_dwordx4 v[48:51], v60, s[8:9]
	global_load_dwordx4 v[52:55], v60, s[2:3]
	v_lshl_add_u64 v[76:77], v[64:65], 0, v[96:97]
	v_lshl_add_u64 v[56:57], v[64:65], 0, v[56:57]
	v_lshl_add_u64 v[58:59], v[64:65], 0, v[58:59]
	v_lshl_add_u64 v[60:61], v[64:65], 0, v[60:61]
	v_lshl_add_u64 v[64:65], v[64:65], 0, v[62:63]
	global_load_dwordx4 v[68:71], v[60:61], off
	s_nop 0
	global_load_dwordx4 v[64:67], v[64:65], off
	s_nop 0
	global_load_dwordx4 v[110:113], v[56:57], off
	global_load_dwordx4 v[72:75], v[58:59], off
	global_load_dwordx4 v[118:121], v[76:77], off offset:2048
	global_load_dwordx4 v[114:117], v[76:77], off offset:3072
	global_load_dwordx4 v[126:129], v[76:77], off
	global_load_dwordx4 v[122:125], v[76:77], off offset:1024
	s_nop 0
	global_load_dwordx4 v[56:59], v62, s[8:9]
	s_nop 0
	global_load_dwordx4 v[60:63], v62, s[2:3]
	v_and_b32_e32 v76, 64, v251
	v_add_u32_e32 v76, 64, v76
	v_xor_b32_e32 v77, 32, v251
	v_cmp_lt_i32_e32 vcc, v77, v76
	s_lshl_b32 s8, s0, 3
	v_lshlrev_b64 v[134:135], 12, v[130:131]
	v_cndmask_b32_e32 v77, v251, v77, vcc
	v_lshlrev_b32_e32 v138, 2, v77
	v_xor_b32_e32 v77, 16, v251
	v_cmp_lt_i32_e32 vcc, v77, v76
	v_lshl_or_b32 v134, v78, 3, v134
	s_ashr_i32 s9, s8, 31
	v_cndmask_b32_e32 v77, v251, v77, vcc
	v_lshlrev_b32_e32 v139, 2, v77
	v_xor_b32_e32 v77, 8, v251
	v_cmp_lt_i32_e32 vcc, v77, v76
	s_lshl_b64 s[10:11], s[8:9], 12
	v_or_b32_e32 v132, v132, v96
	v_cndmask_b32_e32 v77, v251, v77, vcc
	v_lshlrev_b32_e32 v140, 2, v77
	v_xor_b32_e32 v77, 4, v251
	v_cmp_lt_i32_e32 vcc, v77, v76
	s_lshl_b64 s[12:13], s[8:9], 13
	s_mov_b64 s[14:15], 0
	v_cndmask_b32_e32 v77, v251, v77, vcc
	v_lshlrev_b32_e32 v141, 2, v77
	v_xor_b32_e32 v77, 2, v251
	v_cmp_lt_i32_e32 vcc, v77, v76
	s_waitcnt vmcnt(9)
	v_mov_b64_e32 v[100:101], v[70:71]
	v_cndmask_b32_e32 v77, v251, v77, vcc
	v_lshlrev_b32_e32 v142, 2, v77
	v_xor_b32_e32 v77, 1, v251
	v_cmp_lt_i32_e32 vcc, v77, v76
	s_waitcnt vmcnt(8)
	v_mov_b64_e32 v[94:95], v[66:67]
	s_waitcnt vmcnt(6)
	v_mov_b64_e32 v[104:105], v[74:75]
	v_cndmask_b32_e32 v76, v251, v77, vcc
	v_lshlrev_b32_e32 v143, 2, v76
	v_add_u32_e32 v76, s8, v130
	v_ashrrev_i32_e32 v77, 31, v76
	v_lshlrev_b64 v[136:137], 13, v[76:77]
	v_mov_b64_e32 v[106:107], v[110:111]
	s_waitcnt vmcnt(4)
	v_mov_b64_e32 v[76:77], v[114:115]
	v_mov_b64_e32 v[80:81], v[118:119]
	s_waitcnt vmcnt(2)
	v_mov_b64_e32 v[84:85], v[122:123]
	v_mov_b64_e32 v[88:89], v[126:127]
	v_or_b32_e32 v136, v136, v96
	v_mov_b64_e32 v[92:93], v[64:65]
	v_mov_b64_e32 v[98:99], v[68:69]
	v_mov_b64_e32 v[102:103], v[72:73]
	v_mov_b64_e32 v[108:109], v[112:113]
	v_mov_b64_e32 v[78:79], v[116:117]
	v_mov_b64_e32 v[82:83], v[120:121]
	v_mov_b64_e32 v[86:87], v[124:125]
	v_mov_b64_e32 v[90:91], v[128:129]
	s_branch .LBB0_1161
; __device__ __forceinline__ void ln_phase(const float* in, float* outf, bf16_t* outb, const float* g, const float* b, int wv0) {
;     ...
;   for (int row = wv; row < NTOK; row += nwv) {
;     f32x4 v[8]; float s = 0.f;
; #pragma unroll
;     for (int i = 0; i < 8; ++i) v[i] = vn[i];
;     if (row + nwv < NTOK) { const f32x4* ir = (const f32x4*)(in + (size_t)(row + nwv) * DM);
; #pragma unroll
;       for (int i = 0; i < 8; ++i) vn[i] = ir[i * 64 + lane]; }
; #pragma unroll
;     for (int i = 0; i < 8; ++i) s += v[i][0] + v[i][1] + v[i][2] + v[i][3];
;     s = wave_sum(s); const float mu = s * (1.0f / 2048.0f);
;     float sq = 0.f;
; #pragma unroll
;     for (int i = 0; i < 8; ++i) { v[i] -= mu; sq += v[i][0] * v[i][0] + v[i][1] * v[i][1] + v[i][2] * v[i][2] + v[i][3] * v[i][3]; }
;     sq = wave_sum(sq); const float rstd = __builtin_amdgcn_rsqf(sq * (1.0f / 2048.0f) + EPS);
.LBB0_1160:
	s_or_b64 exec, exec, s[16:17]
	v_add_f32_e32 v96, v126, v127
	v_add_f32_e32 v96, v128, v96
	v_add_f32_e32 v131, v122, v123
	v_add_f32_e32 v96, v129, v96
	v_add_f32_e32 v131, v124, v131
	v_add_f32_e32 v96, 0, v96
	v_add_f32_e32 v131, v125, v131
	v_add_f32_e32 v96, v131, v96
	v_add_f32_e32 v131, v118, v119
	v_add_f32_e32 v131, v120, v131
	v_add_f32_e32 v131, v121, v131
	v_add_f32_e32 v96, v131, v96
	v_add_f32_e32 v131, v114, v115
	v_mov_b32_e32 v144, v72
	v_mov_b32_e32 v145, v110
	v_mov_b32_e32 v146, v73
	v_mov_b32_e32 v147, v111
	v_add_f32_e32 v131, v116, v131
	v_pk_add_f32 v[144:145], v[144:145], v[146:147]
	v_mov_b32_e32 v146, v74
	v_mov_b32_e32 v147, v112
	v_add_f32_e32 v131, v117, v131
	v_pk_add_f32 v[144:145], v[146:147], v[144:145]
	v_mov_b32_e32 v146, v75
	v_mov_b32_e32 v147, v113
	v_add_f32_e32 v96, v131, v96
	v_pk_add_f32 v[144:145], v[146:147], v[144:145]
	v_mov_b32_e32 v146, v65
	v_add_f32_e32 v96, v145, v96
	v_add_f32_e32 v96, v144, v96
	v_mov_b32_e32 v144, v64
	v_mov_b32_e32 v145, v68
	v_mov_b32_e32 v147, v69
	v_pk_add_f32 v[144:145], v[144:145], v[146:147]
	v_mov_b32_e32 v146, v66
	v_mov_b32_e32 v147, v70
	v_pk_add_f32 v[144:145], v[146:147], v[144:145]
	v_mov_b32_e32 v146, v67
	v_mov_b32_e32 v147, v71
	v_pk_add_f32 v[144:145], v[146:147], v[144:145]
	s_mov_b32 s0, 0x8900000
	v_add_f32_e32 v96, v145, v96
	v_add_f32_e32 v96, v144, v96
	ds_bpermute_b32 v131, v138, v96
	s_and_b64 s[2:3], exec, s[2:3]
	s_or_b64 s[14:15], s[2:3], s[14:15]
	v_lshl_add_u64 v[136:137], v[136:137], 0, s[12:13]
	s_waitcnt lgkmcnt(0)
	v_add_f32_e32 v96, v96, v131
	ds_bpermute_b32 v131, v139, v96
	s_waitcnt lgkmcnt(0)
	v_add_f32_e32 v96, v96, v131
	ds_bpermute_b32 v131, v140, v96
	s_waitcnt lgkmcnt(0)
	v_add_f32_e32 v96, v96, v131
	ds_bpermute_b32 v131, v141, v96
	s_waitcnt lgkmcnt(0)
	v_add_f32_e32 v96, v96, v131
	ds_bpermute_b32 v131, v142, v96
	s_waitcnt lgkmcnt(0)
	v_add_f32_e32 v96, v96, v131
	ds_bpermute_b32 v131, v143, v96
	s_waitcnt lgkmcnt(0)
	v_add_f32_e32 v96, v96, v131
	v_mul_f32_e32 v156, 0xba000000, v96
	v_fmac_f32_e32 v127, 0xba000000, v96
	v_fmac_f32_e32 v123, 0xba000000, v96
	v_fmamk_f32 v126, v96, 0xba000000, v126
	v_mul_f32_e32 v131, v127, v127
	v_fmamk_f32 v144, v96, 0xba000000, v124
	v_fmamk_f32 v122, v96, 0xba000000, v122
	v_mul_f32_e32 v124, v123, v123
	v_fmac_f32_e32 v119, 0xba000000, v96
	v_fmamk_f32 v128, v96, 0xba000000, v128
	v_fmac_f32_e32 v131, v126, v126
	v_fmac_f32_e32 v124, v122, v122
	v_fmamk_f32 v146, v96, 0xba000000, v120
	v_fmamk_f32 v118, v96, 0xba000000, v118
	v_mul_f32_e32 v120, v119, v119
	v_fmac_f32_e32 v115, 0xba000000, v96
	v_fmamk_f32 v129, v96, 0xba000000, v129
	v_fmac_f32_e32 v131, v128, v128
	v_fmamk_f32 v145, v96, 0xba000000, v125
	v_fmac_f32_e32 v124, v144, v144
	v_fmac_f32_e32 v120, v118, v118
	v_fmamk_f32 v148, v96, 0xba000000, v116
	v_fmamk_f32 v114, v96, 0xba000000, v114
	v_mul_f32_e32 v116, v115, v115
	v_fmac_f32_e32 v111, 0xba000000, v96
	v_fmac_f32_e32 v131, v129, v129
	v_fmac_f32_e32 v124, v145, v145
	v_fmamk_f32 v147, v96, 0xba000000, v121
	v_fmac_f32_e32 v120, v146, v146
	v_fmac_f32_e32 v116, v114, v114
	v_fmamk_f32 v150, v96, 0xba000000, v112
	v_fmamk_f32 v110, v96, 0xba000000, v110
	v_mul_f32_e32 v112, v111, v111
	v_fmac_f32_e32 v73, 0xba000000, v96
	v_fmamk_f32 v69, v96, 0xba000000, v69
	v_fmamk_f32 v65, v96, 0xba000000, v65
	v_add_f32_e32 v124, v131, v124
	v_fmac_f32_e32 v120, v147, v147
	v_fmamk_f32 v149, v96, 0xba000000, v117
	v_fmac_f32_e32 v116, v148, v148
	v_fmamk_f32 v151, v96, 0xba000000, v113
	v_fmac_f32_e32 v112, v110, v110
	v_fmamk_f32 v72, v96, 0xba000000, v72
	v_mul_f32_e32 v113, v73, v73
	v_fmamk_f32 v153, v96, 0xba000000, v71
	v_fmamk_f32 v152, v96, 0xba000000, v70
	v_fmac_f32_e32 v68, 0xba000000, v96
	v_fmac_f32_e32 v64, 0xba000000, v96
	v_mov_b32_e32 v70, v65
	v_mov_b32_e32 v71, v69
	v_add_f32_e32 v120, v120, v124
	v_fmac_f32_e32 v116, v149, v149
	v_fmac_f32_e32 v112, v150, v150
	v_fmamk_f32 v74, v96, 0xba000000, v74
	v_fmac_f32_e32 v113, v72, v72
	v_fmamk_f32 v155, v96, 0xba000000, v67
	v_fmamk_f32 v154, v96, 0xba000000, v66
	v_mov_b32_e32 v66, v64
	v_mov_b32_e32 v67, v68
	v_pk_mul_f32 v[70:71], v[70:71], v[70:71]
	v_add_f32_e32 v116, v116, v120
	v_fmac_f32_e32 v112, v151, v151
	v_fmamk_f32 v75, v96, 0xba000000, v75
	v_fmac_f32_e32 v113, v74, v74
	v_pk_fma_f32 v[66:67], v[66:67], v[66:67], v[70:71]
	v_mov_b32_e32 v70, v154
	v_mov_b32_e32 v71, v152
	v_add_f32_e32 v112, v112, v116
	v_fmac_f32_e32 v113, v75, v75
	v_pk_fma_f32 v[66:67], v[70:71], v[70:71], v[66:67]
	v_mov_b32_e32 v70, v155
	v_mov_b32_e32 v71, v153
	v_add_f32_e32 v112, v113, v112
	v_pk_fma_f32 v[66:67], v[70:71], v[70:71], v[66:67]
	s_nop 0
	v_add_f32_e32 v67, v67, v112
	v_add_f32_e32 v66, v66, v67
	ds_bpermute_b32 v67, v138, v66
	v_lshl_add_u64 v[112:113], s[4:5], 0, v[134:135]
	v_lshl_add_u64 v[134:135], v[134:135], 0, s[10:11]
	s_waitcnt lgkmcnt(0)
; __device__ __forceinline__ void ln_phase(const float* in, float* outf, bf16_t* outb, const float* g, const float* b, int wv0) {
;     ...
;     sq = wave_sum(sq); const float rstd = __builtin_amdgcn_rsqf(sq * (1.0f / 2048.0f) + EPS);
; #pragma unroll
;     for (int i = 0; i < 8; ++i) {
;       const f32x4 y = v[i] * rstd * gg[i] + bb[i];
;       ((f32x4*)(outf + (size_t)row * DM))[i * 64 + lane] = y;
;       if (outb) { u32x2 w; w.x = pk2(y[0], y[1]); w.y = pk2(y[2], y[3]); ((u32x2*)(outb + (size_t)row * DM))[i * 64 + lane] = w; } }
	v_add_f32_e32 v66, v66, v67
	ds_bpermute_b32 v67, v139, v66
	s_waitcnt lgkmcnt(0)
	v_add_f32_e32 v66, v66, v67
	ds_bpermute_b32 v67, v140, v66
	s_waitcnt lgkmcnt(0)
	v_add_f32_e32 v66, v66, v67
	ds_bpermute_b32 v67, v141, v66
	s_waitcnt lgkmcnt(0)
	v_add_f32_e32 v66, v66, v67
	ds_bpermute_b32 v67, v142, v66
	s_waitcnt lgkmcnt(0)
	v_add_f32_e32 v66, v66, v67
	ds_bpermute_b32 v67, v143, v66
	s_waitcnt lgkmcnt(0)
	v_add_f32_e32 v66, v66, v67
	v_fmamk_f32 v66, v66, 0x3a000000, v246
	v_rsq_f32_e32 v96, v66
	s_nop 0
	v_mov_b32_e32 v157, v96
	v_lshrrev_b32_e32 v158, 13, v132
	v_lshlrev_b32_e32 v158, 3, v158
	s_mov_b64 vcc, exec
	s_mov_b64 exec, 1
	global_store_dwordx2 v158, v[156:157], s[100:101]
	s_mov_b64 exec, vcc
	v_pk_mul_f32 v[66:67], v[126:127], v[96:97] op_sel_hi:[1,0]
	v_pk_mul_f32 v[70:71], v[128:129], v[96:97] op_sel_hi:[1,0]
	v_pk_fma_f32 v[124:125], v[0:1], v[66:67], v[8:9]
	v_lshl_add_u64 v[66:67], s[4:5], 0, v[132:133]
	v_pk_fma_f32 v[126:127], v[2:3], v[70:71], v[10:11]
	v_add_co_u32_e32 v70, vcc, s0, v66
	s_mov_b32 s0, 0x8901000
	s_nop 0
	v_addc_co_u32_e32 v71, vcc, 0, v67, vcc
	v_add_co_u32_e32 v128, vcc, s0, v66
	s_mov_b32 s0, 0x4900000
	s_nop 0
	v_addc_co_u32_e32 v129, vcc, 0, v67, vcc
	v_cvt_pk_bf16_f32 v66, v124, v125
	v_cvt_pk_bf16_f32 v67, v126, v127
	v_add_co_u32_e32 v124, vcc, s0, v112
	v_pk_mul_f32 v[64:65], v[64:65], v[96:97] op_sel_hi:[1,0]
	s_nop 0
	v_addc_co_u32_e32 v125, vcc, 0, v113, vcc
	global_store_dwordx2 v[124:125], v[66:67], off
	v_pk_mul_f32 v[66:67], v[122:123], v[96:97] op_sel_hi:[1,0]
	v_pk_mul_f32 v[112:113], v[144:145], v[96:97] op_sel_hi:[1,0]
	v_pk_fma_f32 v[120:121], v[4:5], v[66:67], v[12:13]
	v_pk_fma_f32 v[122:123], v[6:7], v[112:113], v[14:15]
	v_cvt_pk_bf16_f32 v66, v120, v121
	v_cvt_pk_bf16_f32 v67, v122, v123
	global_store_dwordx2 v[124:125], v[66:67], off offset:512
	v_pk_mul_f32 v[66:67], v[118:119], v[96:97] op_sel_hi:[1,0]
	v_pk_mul_f32 v[112:113], v[146:147], v[96:97] op_sel_hi:[1,0]
	v_pk_fma_f32 v[116:117], v[16:17], v[66:67], v[24:25]
	v_pk_fma_f32 v[118:119], v[18:19], v[112:113], v[26:27]
	v_cvt_pk_bf16_f32 v66, v116, v117
	v_cvt_pk_bf16_f32 v67, v118, v119
	global_store_dwordx2 v[124:125], v[66:67], off offset:1024
	v_pk_mul_f32 v[66:67], v[114:115], v[96:97] op_sel_hi:[1,0]
	v_pk_mul_f32 v[112:113], v[148:149], v[96:97] op_sel_hi:[1,0]
	s_waitcnt vmcnt(4)
	v_pk_fma_f32 v[64:65], v[56:57], v[64:65], v[60:61]
	v_pk_fma_f32 v[114:115], v[22:23], v[112:113], v[30:31]
	v_pk_fma_f32 v[112:113], v[20:21], v[66:67], v[28:29]
	v_cvt_pk_bf16_f32 v67, v114, v115
	v_cvt_pk_bf16_f32 v66, v112, v113
	global_store_dwordx2 v[124:125], v[66:67], off offset:1536
	v_pk_mul_f32 v[66:67], v[110:111], v[96:97] op_sel_hi:[1,0]
	v_pk_mul_f32 v[70:71], v[150:151], v[96:97] op_sel_hi:[1,0]
	v_pk_fma_f32 v[110:111], v[32:33], v[66:67], v[36:37]
	v_pk_fma_f32 v[112:113], v[34:35], v[70:71], v[38:39]
	v_cvt_pk_bf16_f32 v66, v110, v111
	v_cvt_pk_bf16_f32 v67, v112, v113
	global_store_dwordx2 v[124:125], v[66:67], off offset:2048
	v_pk_mul_f32 v[66:67], v[72:73], v[96:97] op_sel_hi:[1,0]
	v_pk_mul_f32 v[70:71], v[74:75], v[96:97] op_sel_hi:[1,0]
	v_mov_b64_e32 v[112:113], v[108:109]
	v_pk_fma_f32 v[72:73], v[42:43], v[70:71], v[46:47]
	v_pk_fma_f32 v[70:71], v[40:41], v[66:67], v[44:45]
	v_cvt_pk_bf16_f32 v67, v72, v73
	v_cvt_pk_bf16_f32 v66, v70, v71
	global_store_dwordx2 v[124:125], v[66:67], off offset:2560
	v_pk_mul_f32 v[66:67], v[68:69], v[96:97] op_sel_hi:[1,0]
	v_pk_mul_f32 v[68:69], v[152:153], v[96:97] op_sel_hi:[1,0]
	v_pk_fma_f32 v[66:67], v[48:49], v[66:67], v[52:53]
	v_pk_fma_f32 v[68:69], v[50:51], v[68:69], v[54:55]
	v_mov_b64_e32 v[72:73], v[102:103]
	v_mov_b64_e32 v[116:117], v[78:79]
	v_cvt_pk_bf16_f32 v66, v66, v67
	v_cvt_pk_bf16_f32 v67, v68, v69
	global_store_dwordx2 v[124:125], v[66:67], off offset:3072
	v_pk_mul_f32 v[66:67], v[154:155], v[96:97] op_sel_hi:[1,0]
	v_mov_b64_e32 v[68:69], v[98:99]
	v_pk_fma_f32 v[66:67], v[58:59], v[66:67], v[62:63]
	v_mov_b64_e32 v[120:121], v[82:83]
	v_mov_b64_e32 v[128:129], v[90:91]
	v_cvt_pk_bf16_f32 v64, v64, v65
	v_cvt_pk_bf16_f32 v65, v66, v67
	global_store_dwordx2 v[124:125], v[64:65], off offset:3584
	v_mov_b64_e32 v[64:65], v[92:93]
	v_mov_b64_e32 v[124:125], v[86:87]
	v_lshl_add_u64 v[132:133], v[132:133], 0, s[12:13]
	v_mov_b64_e32 v[66:67], v[94:95]
	v_mov_b64_e32 v[70:71], v[100:101]
	v_mov_b64_e32 v[74:75], v[104:105]
	v_mov_b64_e32 v[110:111], v[106:107]
	v_mov_b64_e32 v[114:115], v[76:77]
	v_mov_b64_e32 v[118:119], v[80:81]
	v_mov_b64_e32 v[122:123], v[84:85]
	v_mov_b64_e32 v[126:127], v[88:89]
	s_andn2_b64 exec, exec, s[14:15]
	s_cbranch_execz .LBB0_1163

; #define PG8_STAGE(bufoff, gbase, voff) do { _Pragma("unroll") for (int _i = 0; _i < 2; ++_i) \
;     __builtin_amdgcn_global_load_lds((const unsigned*)((const char*)(gbase) + (voff)[_i]), (LAS unsigned*)(lds + (bufoff) + ldsw + _i * 8192), 16, 0, 0); } while (0)
; #define PG8_LDA(dst, b, h) do { _Pragma("unroll") for (int m = 0; m < 4; ++m) _Pragma("unroll") for (int k = 0; k < 2; ++k) dst[m][k] = *(const LAS bf16x8*)(lds + PG8_SA(b, h) + aoff + m * 2048 + k * 1024); } while (0)
; #define PG8_LDB(dst, b, h) do { _Pragma("unroll") for (int n = 0; n < 2; ++n) _Pragma("unroll") for (int k = 0; k < 2; ++k) dst[n][k] = *(const LAS bf16x8*)(lds + PG8_SB(b, h) + boff + n * 2048 + k * 1024); } while (0)
; #define PG8_MMA(ai, bj, At, Bt) do { __builtin_amdgcn_s_setprio(1); _Pragma("unroll") for (int m = 0; m < 4; ++m) _Pragma("unroll") for (int n = 0; n < 2; ++n) _Pragma("unroll") for (int k = 0; k < 2; ++k) \
;     acc[ai][bj][m][n] = __builtin_amdgcn_mfma_f32_16x16x32_bf16(Bt[n][k], At[m][k], acc[ai][bj][m][n], 0, 0, 0); __builtin_amdgcn_s_setprio(0); } while (0)
; #define PG8_WAIT_V(n) asm volatile("s_waitcnt vmcnt(" #n ")" ::: "memory")
; #define PG8_WAIT_L(n) asm volatile("s_waitcnt lgkmcnt(" #n ")" ::: "memory")
; #define PG8_BAR __builtin_amdgcn_s_barrier()
; #define PG8_SCHED __builtin_amdgcn_sched_barrier(0)
; template <class Epi>
; __device__ __forceinline__ void gemm_phase(LAS unsigned char* lds, const Gemm g, const StaticOrder& S, const Epi& E, int wv0) {
;     ...
;       PG8_LDB(B0, 0, 0); PG8_SCHED; PG8_LDA(At, 0, 0); PG8_STAGE(PG8_SA(1, 1), a1 + hstepA, voffA);
;       PG8_WAIT_L(8); PG8_BAR; PG8_WAIT_L(0); PG8_MMA(0, 0, At, B0); PG8_BAR; PG8_SCHED;
;       PG8_LDB(B1, 0, 1); PG8_STAGE(PG8_SB(0, 0), b2, voffB);
;       PG8_BAR; PG8_WAIT_L(0); PG8_MMA(0, 1, At, B1); PG8_BAR;
;       PG8_LDA(At, 0, 1); PG8_STAGE(PG8_SA(0, 0), a2, voffA);
;       PG8_BAR; PG8_WAIT_L(0); PG8_MMA(1, 0, At, B0); PG8_BAR; PG8_SCHED;
;       PG8_STAGE(PG8_SB(0, 1), b2 + hstepB, voffB);
;       PG8_WAIT_V(6); PG8_BAR; PG8_MMA(1, 1, At, B1); PG8_BAR;
.LBB0_1429:
	s_add_u32 s14, s12, 0x100
	s_addc_u32 s15, s13, 0
	s_add_i32 s0, 0, 0x10000
	v_add_u32_e32 v142, s0, v187
	ds_read_b128 v[130:133], v142
	ds_read_b128 v[134:137], v142 offset:1024
	ds_read_b128 v[138:141], v142 offset:2048
	ds_read_b128 v[142:145], v142 offset:3072
	s_cmpk_eq_i32 s45, 0x54
	s_cselect_b32 s19, s5, s15
	s_cselect_b32 s18, s4, s14
	s_cselect_b32 s17, s7, s44
	s_cselect_b32 s16, s6, s43
	v_lshl_add_u64 v[184:185], s[12:13], 0, v[168:169]
	s_add_i32 m0, s30, 0xc000
	ds_read_b128 v[146:149], v189
	ds_read_b128 v[150:153], v189 offset:1024
	ds_read_b128 v[154:157], v189 offset:2048
	ds_read_b128 v[158:161], v189 offset:3072
	ds_read_b128 v[172:175], v189 offset:4096
	ds_read_b128 v[176:179], v189 offset:5120
	ds_read_b128 v[180:183], v189 offset:6144
	ds_read_b128 v[190:193], v189 offset:7168
	global_load_lds_dwordx4 v[184:185], off
	v_lshl_add_u64 v[184:185], s[12:13], 0, v[170:171]
	s_add_i32 m0, s30, 0xe000
	s_nop 0
	global_load_lds_dwordx4 v[184:185], off
	s_waitcnt lgkmcnt(8)
	s_barrier
	s_waitcnt lgkmcnt(0)
	s_setprio 1
	s_waitcnt lgkmcnt(0)
	v_mfma_f32_16x16x32_bf16 v[126:129], v[130:133], v[146:149], v[126:129]
	v_mfma_f32_16x16x32_bf16 v[122:125], v[138:141], v[146:149], v[122:125]
	v_mfma_f32_16x16x32_bf16 v[118:121], v[130:133], v[154:157], v[118:121]
	v_mfma_f32_16x16x32_bf16 v[114:117], v[138:141], v[154:157], v[114:117]
	v_mfma_f32_16x16x32_bf16 v[92:95], v[130:133], v[172:175], v[92:95]
	v_mfma_f32_16x16x32_bf16 v[88:91], v[138:141], v[172:175], v[88:91]
	v_mfma_f32_16x16x32_bf16 v[84:87], v[130:133], v[180:183], v[84:87]
	v_mfma_f32_16x16x32_bf16 v[76:79], v[138:141], v[180:183], v[76:79]
	v_mfma_f32_16x16x32_bf16 v[126:129], v[134:137], v[150:153], v[126:129]
	v_mfma_f32_16x16x32_bf16 v[122:125], v[142:145], v[150:153], v[122:125]
	v_mfma_f32_16x16x32_bf16 v[118:121], v[134:137], v[158:161], v[118:121]
	v_mfma_f32_16x16x32_bf16 v[114:117], v[142:145], v[158:161], v[114:117]
	v_mfma_f32_16x16x32_bf16 v[92:95], v[134:137], v[176:179], v[92:95]
	v_mfma_f32_16x16x32_bf16 v[88:91], v[142:145], v[176:179], v[88:91]
	v_mfma_f32_16x16x32_bf16 v[84:87], v[134:137], v[190:193], v[84:87]
	v_mfma_f32_16x16x32_bf16 v[76:79], v[142:145], v[190:193], v[76:79]
	s_setprio 0
	s_barrier
	s_add_i32 s46, 0, 0x14000
	v_add_u32_e32 v184, s46, v187
	s_add_i32 s0, s0, s29
	ds_read_b128 v[194:197], v184
	ds_read_b128 v[198:201], v184 offset:1024
	ds_read_b128 v[202:205], v184 offset:2048
	ds_read_b128 v[206:209], v184 offset:3072
	v_lshl_add_u64 v[184:185], s[16:17], 0, v[96:97]
	s_mov_b32 m0, s0
	v_lshl_add_u64 v[210:211], s[16:17], 0, v[166:167]
	global_load_lds_dwordx4 v[184:185], off
	s_add_i32 m0, s0, 0x2000
	s_nop 0
	global_load_lds_dwordx4 v[210:211], off
	s_barrier
	s_waitcnt lgkmcnt(0)
	s_setprio 1
	s_waitcnt lgkmcnt(0)
	v_mfma_f32_16x16x32_bf16 v[110:113], v[194:197], v[146:149], v[110:113]
	v_mfma_f32_16x16x32_bf16 v[106:109], v[202:205], v[146:149], v[106:109]
	v_mfma_f32_16x16x32_bf16 v[102:105], v[194:197], v[154:157], v[102:105]
	v_mfma_f32_16x16x32_bf16 v[98:101], v[202:205], v[154:157], v[98:101]
	v_mfma_f32_16x16x32_bf16 v[80:83], v[194:197], v[172:175], v[80:83]
	v_mfma_f32_16x16x32_bf16 v[72:75], v[202:205], v[172:175], v[72:75]
	v_mfma_f32_16x16x32_bf16 v[68:71], v[194:197], v[180:183], v[68:71]
	v_mfma_f32_16x16x32_bf16 v[64:67], v[202:205], v[180:183], v[64:67]
	v_mfma_f32_16x16x32_bf16 v[110:113], v[198:201], v[150:153], v[110:113]
	v_mfma_f32_16x16x32_bf16 v[106:109], v[206:209], v[150:153], v[106:109]
	v_mfma_f32_16x16x32_bf16 v[102:105], v[198:201], v[158:161], v[102:105]
	v_mfma_f32_16x16x32_bf16 v[98:101], v[206:209], v[158:161], v[98:101]
	v_mfma_f32_16x16x32_bf16 v[80:83], v[198:201], v[176:179], v[80:83]
	v_mfma_f32_16x16x32_bf16 v[72:75], v[206:209], v[176:179], v[72:75]
	v_mfma_f32_16x16x32_bf16 v[68:71], v[198:201], v[190:193], v[68:71]
	v_mfma_f32_16x16x32_bf16 v[64:67], v[206:209], v[190:193], v[64:67]
	s_setprio 0
	s_mov_b32 m0, s30
	v_lshl_add_u64 v[212:213], s[18:19], 0, v[162:163]
	s_barrier
	ds_read_b128 v[146:149], v189 offset:16384
	ds_read_b128 v[150:153], v189 offset:17408
	ds_read_b128 v[154:157], v189 offset:18432
	ds_read_b128 v[158:161], v189 offset:19456
	ds_read_b128 v[172:175], v189 offset:20480
	ds_read_b128 v[176:179], v189 offset:21504
	ds_read_b128 v[180:183], v189 offset:22528
	ds_read_b128 v[190:193], v189 offset:23552
	global_load_lds_dwordx4 v[212:213], off
	v_lshl_add_u64 v[214:215], s[18:19], 0, v[164:165]
	s_mov_b32 m0, s31
	s_nop 0
	global_load_lds_dwordx4 v[214:215], off
	s_barrier
	s_waitcnt lgkmcnt(0)
	s_setprio 1
	s_waitcnt lgkmcnt(0)
	v_mfma_f32_16x16x32_bf16 v[60:63], v[130:133], v[146:149], v[60:63]
	v_mfma_f32_16x16x32_bf16 v[56:59], v[138:141], v[146:149], v[56:59]
	v_mfma_f32_16x16x32_bf16 v[48:51], v[130:133], v[154:157], v[48:51]
	v_mfma_f32_16x16x32_bf16 v[40:43], v[138:141], v[154:157], v[40:43]
	v_mfma_f32_16x16x32_bf16 v[28:31], v[130:133], v[172:175], v[28:31]
	v_mfma_f32_16x16x32_bf16 v[24:27], v[138:141], v[172:175], v[24:27]
	v_mfma_f32_16x16x32_bf16 v[16:19], v[130:133], v[180:183], v[16:19]
	v_mfma_f32_16x16x32_bf16 v[8:11], v[138:141], v[180:183], v[8:11]
	v_mfma_f32_16x16x32_bf16 v[60:63], v[134:137], v[150:153], v[60:63]
	v_mfma_f32_16x16x32_bf16 v[56:59], v[142:145], v[150:153], v[56:59]
	v_mfma_f32_16x16x32_bf16 v[48:51], v[134:137], v[158:161], v[48:51]
	v_mfma_f32_16x16x32_bf16 v[40:43], v[142:145], v[158:161], v[40:43]
	v_mfma_f32_16x16x32_bf16 v[28:31], v[134:137], v[176:179], v[28:31]
	v_mfma_f32_16x16x32_bf16 v[24:27], v[142:145], v[176:179], v[24:27]
	v_mfma_f32_16x16x32_bf16 v[16:19], v[134:137], v[190:193], v[16:19]
	v_mfma_f32_16x16x32_bf16 v[8:11], v[142:145], v[190:193], v[8:11]
	s_setprio 0
	s_barrier
; #define PG8_STAGE(bufoff, gbase, voff) do { _Pragma("unroll") for (int _i = 0; _i < 2; ++_i) \
;     __builtin_amdgcn_global_load_lds((const unsigned*)((const char*)(gbase) + (voff)[_i]), (LAS unsigned*)(lds + (bufoff) + ldsw + _i * 8192), 16, 0, 0); } while (0)
; #define PG8_LDA(dst, b, h) do { _Pragma("unroll") for (int m = 0; m < 4; ++m) _Pragma("unroll") for (int k = 0; k < 2; ++k) dst[m][k] = *(const LAS bf16x8*)(lds + PG8_SA(b, h) + aoff + m * 2048 + k * 1024); } while (0)
; #define PG8_LDB(dst, b, h) do { _Pragma("unroll") for (int n = 0; n < 2; ++n) _Pragma("unroll") for (int k = 0; k < 2; ++k) dst[n][k] = *(const LAS bf16x8*)(lds + PG8_SB(b, h) + boff + n * 2048 + k * 1024); } while (0)
; #define PG8_MMA(ai, bj, At, Bt) do { __builtin_amdgcn_s_setprio(1); _Pragma("unroll") for (int m = 0; m < 4; ++m) _Pragma("unroll") for (int n = 0; n < 2; ++n) _Pragma("unroll") for (int k = 0; k < 2; ++k) \
;     acc[ai][bj][m][n] = __builtin_amdgcn_mfma_f32_16x16x32_bf16(Bt[n][k], At[m][k], acc[ai][bj][m][n], 0, 0, 0); __builtin_amdgcn_s_setprio(0); } while (0)
; #define PG8_WAIT_V(n) asm volatile("s_waitcnt vmcnt(" #n ")" ::: "memory")
; #define PG8_WAIT_L(n) asm volatile("s_waitcnt lgkmcnt(" #n ")" ::: "memory")
; #define PG8_BAR __builtin_amdgcn_s_barrier()
; #define PG8_SCHED __builtin_amdgcn_sched_barrier(0)
; template <class Epi>
; __device__ __forceinline__ void gemm_phase(LAS unsigned char* lds, const Gemm g, const StaticOrder& S, const Epi& E, int wv0) {
;     ...
;       PG8_LDB(B0, 1, 0); PG8_SCHED; PG8_LDA(At, 1, 0); PG8_STAGE(PG8_SA(0, 1), a2 + hstepA, voffA);
;       PG8_WAIT_L(8); PG8_BAR; PG8_WAIT_L(0); PG8_MMA(0, 0, At, B0); PG8_BAR; PG8_SCHED;
;       PG8_LDB(B1, 1, 1); PG8_STAGE(PG8_SB(1, 0), b3, voffB);
;       PG8_BAR; PG8_WAIT_L(0); PG8_MMA(0, 1, At, B1); PG8_BAR;
;       PG8_LDA(At, 1, 1); PG8_STAGE(PG8_SA(1, 0), a3, voffA);
;       PG8_BAR; PG8_WAIT_L(0); PG8_MMA(1, 0, At, B0); PG8_BAR; PG8_SCHED;
;       PG8_STAGE(PG8_SB(1, 1), b3 + hstepB, voffB);
;       PG8_WAIT_V(6); PG8_BAR; PG8_MMA(1, 1, At, B1); PG8_BAR;
	s_add_u32 s12, s16, 0x160000
	s_addc_u32 s13, s17, 0
	s_add_i32 s0, s46, s29
	v_lshl_add_u64 v[130:131], s[12:13], 0, v[96:97]
	s_mov_b32 m0, s0
	s_nop 0
	global_load_lds_dwordx4 v[130:131], off
	v_lshl_add_u64 v[130:131], s[12:13], 0, v[166:167]
	s_add_i32 m0, s0, 0x2000
	s_nop 0
	global_load_lds_dwordx4 v[130:131], off
	s_waitcnt vmcnt(6)
	s_barrier
	s_setprio 1
	v_mfma_f32_16x16x32_bf16 v[52:55], v[194:197], v[146:149], v[52:55]
	v_mfma_f32_16x16x32_bf16 v[44:47], v[202:205], v[146:149], v[44:47]
	v_mfma_f32_16x16x32_bf16 v[36:39], v[194:197], v[154:157], v[36:39]
	v_mfma_f32_16x16x32_bf16 v[32:35], v[202:205], v[154:157], v[32:35]
	v_mfma_f32_16x16x32_bf16 v[20:23], v[194:197], v[172:175], v[20:23]
	v_mfma_f32_16x16x32_bf16 v[12:15], v[202:205], v[172:175], v[12:15]
	v_mfma_f32_16x16x32_bf16 v[4:7], v[194:197], v[180:183], v[4:7]
	v_mfma_f32_16x16x32_bf16 v[0:3], v[202:205], v[180:183], v[0:3]
	v_mfma_f32_16x16x32_bf16 v[52:55], v[198:201], v[150:153], v[52:55]
	v_mfma_f32_16x16x32_bf16 v[44:47], v[206:209], v[150:153], v[44:47]
	v_mfma_f32_16x16x32_bf16 v[36:39], v[198:201], v[158:161], v[36:39]
	v_mfma_f32_16x16x32_bf16 v[32:35], v[206:209], v[158:161], v[32:35]
	v_mfma_f32_16x16x32_bf16 v[20:23], v[198:201], v[176:179], v[20:23]
	v_mfma_f32_16x16x32_bf16 v[12:15], v[206:209], v[176:179], v[12:15]
	v_mfma_f32_16x16x32_bf16 v[4:7], v[198:201], v[190:193], v[4:7]
	v_mfma_f32_16x16x32_bf16 v[0:3], v[206:209], v[190:193], v[0:3]
	s_setprio 0
	s_add_i32 s0, 0, 0x18000
	v_add_u32_e32 v142, s0, v187
	s_barrier
	ds_read_b128 v[130:133], v142
	ds_read_b128 v[134:137], v142 offset:1024
	ds_read_b128 v[138:141], v142 offset:2048
	ds_read_b128 v[142:145], v142 offset:3072
	s_add_u32 s12, s18, 0x160000
	s_addc_u32 s13, s19, 0
	s_mov_b32 m0, s34
	v_lshl_add_u64 v[194:195], s[12:13], 0, v[162:163]
	ds_read_b128 v[146:149], v189 offset:32768
	ds_read_b128 v[150:153], v189 offset:33792
	ds_read_b128 v[154:157], v189 offset:34816
	ds_read_b128 v[158:161], v189 offset:35840
	ds_read_b128 v[172:175], v189 offset:36864
	ds_read_b128 v[176:179], v189 offset:37888
	ds_read_b128 v[180:183], v189 offset:38912
	ds_read_b128 v[190:193], v189 offset:39936
	global_load_lds_dwordx4 v[194:195], off
	v_lshl_add_u64 v[194:195], s[12:13], 0, v[164:165]
	s_mov_b32 m0, s35
	s_nop 0
	global_load_lds_dwordx4 v[194:195], off
	s_waitcnt lgkmcnt(8)
	s_barrier
	s_waitcnt lgkmcnt(0)
	s_setprio 1
	s_waitcnt lgkmcnt(0)
	v_mfma_f32_16x16x32_bf16 v[126:129], v[130:133], v[146:149], v[126:129]
	v_mfma_f32_16x16x32_bf16 v[122:125], v[138:141], v[146:149], v[122:125]
	v_mfma_f32_16x16x32_bf16 v[118:121], v[130:133], v[154:157], v[118:121]
	v_mfma_f32_16x16x32_bf16 v[114:117], v[138:141], v[154:157], v[114:117]
	v_mfma_f32_16x16x32_bf16 v[92:95], v[130:133], v[172:175], v[92:95]
	v_mfma_f32_16x16x32_bf16 v[88:91], v[138:141], v[172:175], v[88:91]
	v_mfma_f32_16x16x32_bf16 v[84:87], v[130:133], v[180:183], v[84:87]
	v_mfma_f32_16x16x32_bf16 v[76:79], v[138:141], v[180:183], v[76:79]
	v_mfma_f32_16x16x32_bf16 v[126:129], v[134:137], v[150:153], v[126:129]
	v_mfma_f32_16x16x32_bf16 v[122:125], v[142:145], v[150:153], v[122:125]
	v_mfma_f32_16x16x32_bf16 v[118:121], v[134:137], v[158:161], v[118:121]
	v_mfma_f32_16x16x32_bf16 v[114:117], v[142:145], v[158:161], v[114:117]
	v_mfma_f32_16x16x32_bf16 v[92:95], v[134:137], v[176:179], v[92:95]
	v_mfma_f32_16x16x32_bf16 v[88:91], v[142:145], v[176:179], v[88:91]
	v_mfma_f32_16x16x32_bf16 v[84:87], v[134:137], v[190:193], v[84:87]
	v_mfma_f32_16x16x32_bf16 v[76:79], v[142:145], v[190:193], v[76:79]
	s_setprio 0
	s_barrier
	s_add_i32 s18, 0, 0x1c000
	s_add_i32 s0, s0, s29
	v_add_u32_e32 v206, s18, v187
	v_lshl_add_u64 v[184:185], v[184:185], 0, s[72:73]
	s_mov_b32 m0, s0
	ds_read_b128 v[194:197], v206
	ds_read_b128 v[198:201], v206 offset:1024
	ds_read_b128 v[202:205], v206 offset:2048
	ds_read_b128 v[206:209], v206 offset:3072
	global_load_lds_dwordx4 v[184:185], off
	v_lshl_add_u64 v[184:185], v[210:211], 0, s[72:73]
	s_add_i32 m0, s0, 0x2000
	s_nop 0
	global_load_lds_dwordx4 v[184:185], off
	s_barrier
	s_waitcnt lgkmcnt(0)
	s_setprio 1
	s_waitcnt lgkmcnt(0)
	v_mfma_f32_16x16x32_bf16 v[110:113], v[194:197], v[146:149], v[110:113]
	v_mfma_f32_16x16x32_bf16 v[106:109], v[202:205], v[146:149], v[106:109]
	v_mfma_f32_16x16x32_bf16 v[102:105], v[194:197], v[154:157], v[102:105]
	v_mfma_f32_16x16x32_bf16 v[98:101], v[202:205], v[154:157], v[98:101]
	v_mfma_f32_16x16x32_bf16 v[80:83], v[194:197], v[172:175], v[80:83]
	v_mfma_f32_16x16x32_bf16 v[72:75], v[202:205], v[172:175], v[72:75]
	v_mfma_f32_16x16x32_bf16 v[68:71], v[194:197], v[180:183], v[68:71]
	v_mfma_f32_16x16x32_bf16 v[64:67], v[202:205], v[180:183], v[64:67]
	v_mfma_f32_16x16x32_bf16 v[110:113], v[198:201], v[150:153], v[110:113]
	v_mfma_f32_16x16x32_bf16 v[106:109], v[206:209], v[150:153], v[106:109]
	v_mfma_f32_16x16x32_bf16 v[102:105], v[198:201], v[158:161], v[102:105]
	v_mfma_f32_16x16x32_bf16 v[98:101], v[206:209], v[158:161], v[98:101]
	v_mfma_f32_16x16x32_bf16 v[80:83], v[198:201], v[176:179], v[80:83]
	v_mfma_f32_16x16x32_bf16 v[72:75], v[206:209], v[176:179], v[72:75]
	v_mfma_f32_16x16x32_bf16 v[68:71], v[198:201], v[190:193], v[68:71]
	v_mfma_f32_16x16x32_bf16 v[64:67], v[206:209], v[190:193], v[64:67]
	s_setprio 0
	s_mov_b32 m0, s36
	v_lshl_add_u64 v[184:185], v[212:213], 0, s[72:73]
	s_barrier
	ds_read_b128 v[146:149], v189 offset:49152
	ds_read_b128 v[150:153], v189 offset:50176
	ds_read_b128 v[154:157], v189 offset:51200
	ds_read_b128 v[158:161], v189 offset:52224
	ds_read_b128 v[172:175], v189 offset:53248
	ds_read_b128 v[176:179], v189 offset:54272
	ds_read_b128 v[180:183], v189 offset:55296
	ds_read_b128 v[190:193], v189 offset:56320
	global_load_lds_dwordx4 v[184:185], off
	v_lshl_add_u64 v[184:185], v[214:215], 0, s[72:73]
	s_mov_b32 m0, s37
	s_nop 0
	global_load_lds_dwordx4 v[184:185], off
	s_barrier
; template <class Epi>
; __device__ __forceinline__ void gemm_phase(LAS unsigned char* lds, const Gemm g, const StaticOrder& S, const Epi& E, int wv0) {
;     ...
;       PG8_LDB(B0, 0, 0); PG8_SCHED; PG8_LDA(At, 0, 0); PG8_STAGE(PG8_SA(1, 1), a1 + hstepA, voffA);
;       PG8_WAIT_L(8); PG8_BAR; PG8_WAIT_L(0); PG8_MMA(0, 0, At, B0); PG8_BAR; PG8_SCHED;
;       PG8_LDB(B1, 0, 1); PG8_STAGE(PG8_SB(0, 0), b2, voffB);
;       PG8_BAR; PG8_WAIT_L(0); PG8_MMA(0, 1, At, B1); PG8_BAR;
;       PG8_LDA(At, 0, 1); PG8_STAGE(PG8_SA(0, 0), a2, voffA);
;       PG8_BAR; PG8_WAIT_L(0); PG8_MMA(1, 0, At, B0); PG8_BAR; PG8_SCHED;
;       PG8_STAGE(PG8_SB(0, 1), b2 + hstepB, voffB);
;       PG8_WAIT_V(6); PG8_BAR; PG8_MMA(1, 1, At, B1); PG8_BAR;
;       PG8_LDB(B0, 1, 0); PG8_SCHED; PG8_LDA(At, 1, 0); PG8_STAGE(PG8_SA(0, 1), a2 + hstepA, voffA);
;       PG8_WAIT_L(8); PG8_BAR; PG8_WAIT_L(0); PG8_MMA(0, 0, At, B0); PG8_BAR; PG8_SCHED;
;       PG8_LDB(B1, 1, 1); PG8_STAGE(PG8_SB(1, 0), b3, voffB);
;       PG8_BAR; PG8_WAIT_L(0); PG8_MMA(0, 1, At, B1); PG8_BAR;
;       PG8_LDA(At, 1, 1); PG8_STAGE(PG8_SA(1, 0), a3, voffA);
;       PG8_BAR; PG8_WAIT_L(0); PG8_MMA(1, 0, At, B0); PG8_BAR; PG8_SCHED;
;       PG8_STAGE(PG8_SB(1, 1), b3 + hstepB, voffB);
;       PG8_WAIT_V(6); PG8_BAR; PG8_MMA(1, 1, At, B1); PG8_BAR;
;   __device__ __forceinline__ void operator()(const f32x4 (&acc)[2][2][4][2], const pg8::Unit& u, int wr, int wc, int fr, int fq) const {
;     ...
;     const int row0 = u.pm * 256 + wr * 64 + fr, col0 = u.pn * 256 + wc * 32 + 8 * fq;
;     f32x4 hb[2][2]; float hs[2][4];
; #pragma unroll
;     for (int bj = 0; bj < 2; ++bj) { hb[bj][0] = (f32x4){0.f, 0.f, 0.f, 0.f}; hb[bj][1] = hb[bj][0];
;       if (MODE == E_GATE) { hb[bj][0] = *(const f32x4*)(e.f0 + col0 + bj * 128) * (-LOG2E); hb[bj][1] = *(const f32x4*)(e.f0 + col0 + bj * 128 + 4) * (-LOG2E); } }
; #pragma unroll
;     for (int ai = 0; ai < 2; ++ai)
; #pragma unroll
;       for (int m = 0; m < 4; ++m) { hs[ai][m] = 0.f;
;         if (MODE == E_UQ) hs[ai][m] = ((const f32x4*)e.f0)[row0 + ai * 128 + m * 16].x * MLA_QSCALE;
;         if (MODE == E_UKV) hs[ai][m] = ((const f32x4*)e.f0)[row0 + ai * 128 + m * 16].y; }
;     EpiPre q[2][4];
; #pragma unroll
;     for (int i = 0; i < 4; ++i) preload(q[0][i], row0 + (i >> 1) * 16, col0 + (i & 1) * 128);
; #pragma unroll
;     for (int gi = 0; gi < 4; ++gi) {
	s_waitcnt lgkmcnt(0)
	s_setprio 1
	s_waitcnt lgkmcnt(0)
	v_mfma_f32_16x16x32_bf16 v[60:63], v[130:133], v[146:149], v[60:63]
	v_mfma_f32_16x16x32_bf16 v[56:59], v[138:141], v[146:149], v[56:59]
	v_mfma_f32_16x16x32_bf16 v[48:51], v[130:133], v[154:157], v[48:51]
	v_mfma_f32_16x16x32_bf16 v[40:43], v[138:141], v[154:157], v[40:43]
	v_mfma_f32_16x16x32_bf16 v[28:31], v[130:133], v[172:175], v[28:31]
	v_mfma_f32_16x16x32_bf16 v[24:27], v[138:141], v[172:175], v[24:27]
	v_mfma_f32_16x16x32_bf16 v[16:19], v[130:133], v[180:183], v[16:19]
	v_mfma_f32_16x16x32_bf16 v[8:11], v[138:141], v[180:183], v[8:11]
	v_mfma_f32_16x16x32_bf16 v[60:63], v[134:137], v[150:153], v[60:63]
	v_mfma_f32_16x16x32_bf16 v[56:59], v[142:145], v[150:153], v[56:59]
	v_mfma_f32_16x16x32_bf16 v[48:51], v[134:137], v[158:161], v[48:51]
	v_mfma_f32_16x16x32_bf16 v[40:43], v[142:145], v[158:161], v[40:43]
	v_mfma_f32_16x16x32_bf16 v[28:31], v[134:137], v[176:179], v[28:31]
	v_mfma_f32_16x16x32_bf16 v[24:27], v[142:145], v[176:179], v[24:27]
	v_mfma_f32_16x16x32_bf16 v[16:19], v[134:137], v[190:193], v[16:19]
	v_mfma_f32_16x16x32_bf16 v[8:11], v[142:145], v[190:193], v[8:11]
	s_setprio 0
	s_barrier
	s_add_u32 s12, s16, 0x160080
	s_addc_u32 s13, s17, 0
	s_add_i32 s0, s18, s29
	v_lshl_add_u64 v[130:131], s[12:13], 0, v[96:97]
	s_mov_b32 m0, s0
	s_nop 0
	global_load_lds_dwordx4 v[130:131], off
	v_lshl_add_u64 v[130:131], s[12:13], 0, v[166:167]
	s_add_i32 m0, s0, 0x2000
	s_nop 0
	global_load_lds_dwordx4 v[130:131], off
	s_waitcnt vmcnt(6)
	s_barrier
	s_setprio 1
	v_mfma_f32_16x16x32_bf16 v[52:55], v[194:197], v[146:149], v[52:55]
	v_mfma_f32_16x16x32_bf16 v[44:47], v[202:205], v[146:149], v[44:47]
	v_mfma_f32_16x16x32_bf16 v[36:39], v[194:197], v[154:157], v[36:39]
	v_mfma_f32_16x16x32_bf16 v[32:35], v[202:205], v[154:157], v[32:35]
	v_mfma_f32_16x16x32_bf16 v[20:23], v[194:197], v[172:175], v[20:23]
	v_mfma_f32_16x16x32_bf16 v[12:15], v[202:205], v[172:175], v[12:15]
	v_mfma_f32_16x16x32_bf16 v[4:7], v[194:197], v[180:183], v[4:7]
	v_mfma_f32_16x16x32_bf16 v[0:3], v[202:205], v[180:183], v[0:3]
	v_mfma_f32_16x16x32_bf16 v[52:55], v[198:201], v[150:153], v[52:55]
	v_mfma_f32_16x16x32_bf16 v[44:47], v[206:209], v[150:153], v[44:47]
	v_mfma_f32_16x16x32_bf16 v[36:39], v[198:201], v[158:161], v[36:39]
	v_mfma_f32_16x16x32_bf16 v[32:35], v[206:209], v[158:161], v[32:35]
	v_mfma_f32_16x16x32_bf16 v[20:23], v[198:201], v[176:179], v[20:23]
	v_mfma_f32_16x16x32_bf16 v[12:15], v[206:209], v[176:179], v[12:15]
	v_mfma_f32_16x16x32_bf16 v[4:7], v[198:201], v[190:193], v[4:7]
	v_mfma_f32_16x16x32_bf16 v[0:3], v[206:209], v[190:193], v[0:3]
	s_setprio 0
	s_add_i32 s45, s45, 2
	s_add_u32 s43, s43, 0x100
	s_addc_u32 s44, s44, 0
	s_cmpk_gt_u32 s45, 0x55
	s_mov_b64 s[12:13], s[14:15]
	s_barrier
	s_cbranch_scc0 .LBB0_1429
	s_load_dwordx4 s[16:19], s[54:55], 0x88
	v_lshl_add_u32 v252, s1, 8, v186
	v_lshl_or_b32 v218, s42, 8, v188
	v_lshlrev_b32_e32 v247, 13, v252
	v_lshlrev_b32_e32 v218, 2, v218
	v_lshlrev_b32_e32 v252, 3, v252
	v_add_u32_e32 v247, v247, v218
	s_add_u32 s12, s8, 0x27700000
	s_addc_u32 s13, s9, 0
	s_add_u32 s14, s10, 0x0
	s_addc_u32 s15, s11, 0
	global_load_dwordx2 v[184:185], v252, s[12:13] offset:0
	global_load_dwordx4 v[130:133], v247, s[14:15]
	global_load_dwordx4 v[134:137], v247, s[14:15] offset:16
	global_load_dwordx4 v[138:141], v247, s[14:15] offset:512
	global_load_dwordx4 v[142:145], v247, s[14:15] offset:528
	s_add_u32 s44, s10, 0x20000
	s_addc_u32 s45, s11, 0
	global_load_dwordx2 v[242:243], v252, s[12:13] offset:128
	global_load_dwordx4 v[146:149], v247, s[44:45]
	global_load_dwordx4 v[150:153], v247, s[44:45] offset:16
	global_load_dwordx4 v[154:157], v247, s[44:45] offset:512
	global_load_dwordx4 v[158:161], v247, s[44:45] offset:528
	s_add_u32 s46, s10, 0x40000
	s_addc_u32 s47, s11, 0
	global_load_dwordx2 v[248:249], v252, s[12:13] offset:256
	global_load_dwordx4 v[172:175], v247, s[46:47]
	global_load_dwordx4 v[176:179], v247, s[46:47] offset:16
	global_load_dwordx4 v[180:183], v247, s[46:47] offset:512
	global_load_dwordx4 v[238:241], v247, s[46:47] offset:528
	s_lshl_b32 s0, s66, 13
	s_waitcnt lgkmcnt(0)
	s_add_u32 s16, s16, s0
	s_addc_u32 s17, s17, 0
	s_add_u32 s18, s18, s0
	s_addc_u32 s19, s19, 0
	global_load_dwordx4 v[190:193], v218, s[16:17]
	global_load_dwordx4 v[194:197], v218, s[16:17] offset:16
	global_load_dwordx4 v[198:201], v218, s[16:17] offset:512
	global_load_dwordx4 v[202:205], v218, s[16:17] offset:528
	global_load_dwordx4 v[206:209], v218, s[18:19]
	global_load_dwordx4 v[210:213], v218, s[18:19] offset:16
	global_load_dwordx4 v[214:217], v218, s[18:19] offset:512
	global_load_dwordx4 v[234:237], v218, s[18:19] offset:528
	s_waitcnt vmcnt(0)
;   __device__ __forceinline__ void emit(const EpiPre& q0, int row, int col, f32x4 a, f32x4 b, const f32x4 (&hb)[2][2], const float (&hs)[2][4], int ai_, int m_, int bj_) const {
;     ...
;     } else if (MODE == E_RES) {
;       const f32x4 r0 = q.a0, r1 = q.a1;
;       float* o = (float*)e.out + (size_t)row * DM + col;
;       *(f32x4*)o = (f32x4){ALPHA * r0[0] + v[0], ALPHA * r0[1] + v[1], ALPHA * r0[2] + v[2], ALPHA * r0[3] + v[3]};
;       *(f32x4*)(o + 4) = (f32x4){ALPHA * r1[0] + v[4], ALPHA * r1[1] + v[5], ALPHA * r1[2] + v[6], ALPHA * r1[3] + v[7]};
; __device__ __forceinline__ void ln_phase(const float* in, float* outf, bf16_t* outb, const float* g, const float* b, int wv0) {
;     ...
; #pragma unroll
;     for (int i = 0; i < 8; ++i) {
;       const f32x4 y = v[i] * rstd * gg[i] + bb[i];
	v_pk_add_f32 v[130:131], v[130:131], v[184:185] op_sel_hi:[1,0]
	v_pk_add_f32 v[132:133], v[132:133], v[184:185] op_sel_hi:[1,0]
	v_pk_add_f32 v[134:135], v[134:135], v[184:185] op_sel_hi:[1,0]
	v_pk_add_f32 v[136:137], v[136:137], v[184:185] op_sel_hi:[1,0]
	v_pk_add_f32 v[138:139], v[138:139], v[184:185] op_sel_hi:[1,0]
	v_pk_add_f32 v[140:141], v[140:141], v[184:185] op_sel_hi:[1,0]
	v_pk_add_f32 v[142:143], v[142:143], v[184:185] op_sel_hi:[1,0]
	v_pk_add_f32 v[144:145], v[144:145], v[184:185] op_sel_hi:[1,0]
	v_pk_mul_f32 v[130:131], v[130:131], v[184:185] op_sel:[0,1] op_sel_hi:[1,1]
	v_pk_mul_f32 v[132:133], v[132:133], v[184:185] op_sel:[0,1] op_sel_hi:[1,1]
	v_pk_mul_f32 v[134:135], v[134:135], v[184:185] op_sel:[0,1] op_sel_hi:[1,1]
	v_pk_mul_f32 v[136:137], v[136:137], v[184:185] op_sel:[0,1] op_sel_hi:[1,1]
	v_pk_mul_f32 v[138:139], v[138:139], v[184:185] op_sel:[0,1] op_sel_hi:[1,1]
	v_pk_mul_f32 v[140:141], v[140:141], v[184:185] op_sel:[0,1] op_sel_hi:[1,1]
	v_pk_mul_f32 v[142:143], v[142:143], v[184:185] op_sel:[0,1] op_sel_hi:[1,1]
	v_pk_mul_f32 v[144:145], v[144:145], v[184:185] op_sel:[0,1] op_sel_hi:[1,1]
	v_pk_fma_f32 v[130:131], v[190:191], v[130:131], v[206:207]
	v_pk_fma_f32 v[132:133], v[192:193], v[132:133], v[208:209]
	v_pk_fma_f32 v[134:135], v[194:195], v[134:135], v[210:211]
	v_pk_fma_f32 v[136:137], v[196:197], v[136:137], v[212:213]
	v_pk_fma_f32 v[138:139], v[198:199], v[138:139], v[214:215]
	v_pk_fma_f32 v[140:141], v[200:201], v[140:141], v[216:217]
	v_pk_fma_f32 v[142:143], v[202:203], v[142:143], v[234:235]
	v_pk_fma_f32 v[144:145], v[204:205], v[144:145], v[236:237]
	v_pk_fma_f32 v[126:127], v[130:131], s[90:91], v[126:127] op_sel_hi:[1,0,1]
	v_pk_fma_f32 v[128:129], v[132:133], s[90:91], v[128:129] op_sel_hi:[1,0,1]
	v_pk_fma_f32 v[122:123], v[134:135], s[90:91], v[122:123] op_sel_hi:[1,0,1]
	v_pk_fma_f32 v[124:125], v[136:137], s[90:91], v[124:125] op_sel_hi:[1,0,1]
	v_pk_fma_f32 v[110:111], v[138:139], s[90:91], v[110:111] op_sel_hi:[1,0,1]
	v_pk_fma_f32 v[112:113], v[140:141], s[90:91], v[112:113] op_sel_hi:[1,0,1]
	v_pk_fma_f32 v[106:107], v[142:143], s[90:91], v[106:107] op_sel_hi:[1,0,1]
	v_pk_fma_f32 v[108:109], v[144:145], s[90:91], v[108:109] op_sel_hi:[1,0,1]
	s_add_u32 s48, s10, 0x60000
	s_addc_u32 s49, s11, 0
	global_load_dwordx2 v[184:185], v252, s[12:13] offset:384
	global_load_dwordx4 v[130:133], v247, s[48:49]
	global_load_dwordx4 v[134:137], v247, s[48:49] offset:16
	global_load_dwordx4 v[138:141], v247, s[48:49] offset:512
	global_load_dwordx4 v[142:145], v247, s[48:49] offset:528
	s_waitcnt vmcnt(18)
	v_pk_add_f32 v[146:147], v[146:147], v[242:243] op_sel_hi:[1,0]
	v_pk_add_f32 v[148:149], v[148:149], v[242:243] op_sel_hi:[1,0]
	v_pk_add_f32 v[150:151], v[150:151], v[242:243] op_sel_hi:[1,0]
	v_pk_add_f32 v[152:153], v[152:153], v[242:243] op_sel_hi:[1,0]
	v_pk_add_f32 v[154:155], v[154:155], v[242:243] op_sel_hi:[1,0]
	v_pk_add_f32 v[156:157], v[156:157], v[242:243] op_sel_hi:[1,0]
	v_pk_add_f32 v[158:159], v[158:159], v[242:243] op_sel_hi:[1,0]
	v_pk_add_f32 v[160:161], v[160:161], v[242:243] op_sel_hi:[1,0]
	v_pk_mul_f32 v[146:147], v[146:147], v[242:243] op_sel:[0,1] op_sel_hi:[1,1]
	v_pk_mul_f32 v[148:149], v[148:149], v[242:243] op_sel:[0,1] op_sel_hi:[1,1]
	v_pk_mul_f32 v[150:151], v[150:151], v[242:243] op_sel:[0,1] op_sel_hi:[1,1]
	v_pk_mul_f32 v[152:153], v[152:153], v[242:243] op_sel:[0,1] op_sel_hi:[1,1]
	v_pk_mul_f32 v[154:155], v[154:155], v[242:243] op_sel:[0,1] op_sel_hi:[1,1]
	v_pk_mul_f32 v[156:157], v[156:157], v[242:243] op_sel:[0,1] op_sel_hi:[1,1]
	v_pk_mul_f32 v[158:159], v[158:159], v[242:243] op_sel:[0,1] op_sel_hi:[1,1]
	v_pk_mul_f32 v[160:161], v[160:161], v[242:243] op_sel:[0,1] op_sel_hi:[1,1]
	v_pk_fma_f32 v[146:147], v[190:191], v[146:147], v[206:207]
	v_pk_fma_f32 v[148:149], v[192:193], v[148:149], v[208:209]
	v_pk_fma_f32 v[150:151], v[194:195], v[150:151], v[210:211]
	v_pk_fma_f32 v[152:153], v[196:197], v[152:153], v[212:213]
	v_pk_fma_f32 v[154:155], v[198:199], v[154:155], v[214:215]
	v_pk_fma_f32 v[156:157], v[200:201], v[156:157], v[216:217]
	v_pk_fma_f32 v[158:159], v[202:203], v[158:159], v[234:235]
	v_pk_fma_f32 v[160:161], v[204:205], v[160:161], v[236:237]
	v_pk_fma_f32 v[118:119], v[146:147], s[90:91], v[118:119] op_sel_hi:[1,0,1]
	v_pk_fma_f32 v[120:121], v[148:149], s[90:91], v[120:121] op_sel_hi:[1,0,1]
	v_pk_fma_f32 v[114:115], v[150:151], s[90:91], v[114:115] op_sel_hi:[1,0,1]
	v_pk_fma_f32 v[116:117], v[152:153], s[90:91], v[116:117] op_sel_hi:[1,0,1]
	v_pk_fma_f32 v[102:103], v[154:155], s[90:91], v[102:103] op_sel_hi:[1,0,1]
	v_pk_fma_f32 v[104:105], v[156:157], s[90:91], v[104:105] op_sel_hi:[1,0,1]
	v_pk_fma_f32 v[98:99], v[158:159], s[90:91], v[98:99] op_sel_hi:[1,0,1]
	v_pk_fma_f32 v[100:101], v[160:161], s[90:91], v[100:101] op_sel_hi:[1,0,1]
	s_add_u32 s16, s10, 0x100000
	s_addc_u32 s17, s11, 0
	global_load_dwordx2 v[242:243], v252, s[12:13] offset:1024
	global_load_dwordx4 v[146:149], v247, s[16:17]
	global_load_dwordx4 v[150:153], v247, s[16:17] offset:16
	global_load_dwordx4 v[154:157], v247, s[16:17] offset:512
	global_load_dwordx4 v[158:161], v247, s[16:17] offset:528
	s_waitcnt vmcnt(18)
;   __device__ __forceinline__ void emit(const EpiPre& q0, int row, int col, f32x4 a, f32x4 b, const f32x4 (&hb)[2][2], const float (&hs)[2][4], int ai_, int m_, int bj_) const {
;     ...
;     } else if (MODE == E_RES) {
;       const f32x4 r0 = q.a0, r1 = q.a1;
;       float* o = (float*)e.out + (size_t)row * DM + col;
;       *(f32x4*)o = (f32x4){ALPHA * r0[0] + v[0], ALPHA * r0[1] + v[1], ALPHA * r0[2] + v[2], ALPHA * r0[3] + v[3]};
;       *(f32x4*)(o + 4) = (f32x4){ALPHA * r1[0] + v[4], ALPHA * r1[1] + v[5], ALPHA * r1[2] + v[6], ALPHA * r1[3] + v[7]};
; __device__ __forceinline__ void ln_phase(const float* in, float* outf, bf16_t* outb, const float* g, const float* b, int wv0) {
;     ...
; #pragma unroll
;     for (int i = 0; i < 8; ++i) {
;       const f32x4 y = v[i] * rstd * gg[i] + bb[i];
	v_pk_add_f32 v[172:173], v[172:173], v[248:249] op_sel_hi:[1,0]
	v_pk_add_f32 v[174:175], v[174:175], v[248:249] op_sel_hi:[1,0]
	v_pk_add_f32 v[176:177], v[176:177], v[248:249] op_sel_hi:[1,0]
	v_pk_add_f32 v[178:179], v[178:179], v[248:249] op_sel_hi:[1,0]
	v_pk_add_f32 v[180:181], v[180:181], v[248:249] op_sel_hi:[1,0]
	v_pk_add_f32 v[182:183], v[182:183], v[248:249] op_sel_hi:[1,0]
	v_pk_add_f32 v[238:239], v[238:239], v[248:249] op_sel_hi:[1,0]
	v_pk_add_f32 v[240:241], v[240:241], v[248:249] op_sel_hi:[1,0]
	v_pk_mul_f32 v[172:173], v[172:173], v[248:249] op_sel:[0,1] op_sel_hi:[1,1]
	v_pk_mul_f32 v[174:175], v[174:175], v[248:249] op_sel:[0,1] op_sel_hi:[1,1]
	v_pk_mul_f32 v[176:177], v[176:177], v[248:249] op_sel:[0,1] op_sel_hi:[1,1]
	v_pk_mul_f32 v[178:179], v[178:179], v[248:249] op_sel:[0,1] op_sel_hi:[1,1]
	v_pk_mul_f32 v[180:181], v[180:181], v[248:249] op_sel:[0,1] op_sel_hi:[1,1]
	v_pk_mul_f32 v[182:183], v[182:183], v[248:249] op_sel:[0,1] op_sel_hi:[1,1]
	v_pk_mul_f32 v[238:239], v[238:239], v[248:249] op_sel:[0,1] op_sel_hi:[1,1]
	v_pk_mul_f32 v[240:241], v[240:241], v[248:249] op_sel:[0,1] op_sel_hi:[1,1]
	v_pk_fma_f32 v[172:173], v[190:191], v[172:173], v[206:207]
	v_pk_fma_f32 v[174:175], v[192:193], v[174:175], v[208:209]
	v_pk_fma_f32 v[176:177], v[194:195], v[176:177], v[210:211]
	v_pk_fma_f32 v[178:179], v[196:197], v[178:179], v[212:213]
	v_pk_fma_f32 v[180:181], v[198:199], v[180:181], v[214:215]
	v_pk_fma_f32 v[182:183], v[200:201], v[182:183], v[216:217]
	v_pk_fma_f32 v[238:239], v[202:203], v[238:239], v[234:235]
	v_pk_fma_f32 v[240:241], v[204:205], v[240:241], v[236:237]
	v_pk_fma_f32 v[92:93], v[172:173], s[90:91], v[92:93] op_sel_hi:[1,0,1]
	v_pk_fma_f32 v[94:95], v[174:175], s[90:91], v[94:95] op_sel_hi:[1,0,1]
	v_pk_fma_f32 v[88:89], v[176:177], s[90:91], v[88:89] op_sel_hi:[1,0,1]
	v_pk_fma_f32 v[90:91], v[178:179], s[90:91], v[90:91] op_sel_hi:[1,0,1]
	v_pk_fma_f32 v[80:81], v[180:181], s[90:91], v[80:81] op_sel_hi:[1,0,1]
	v_pk_fma_f32 v[82:83], v[182:183], s[90:91], v[82:83] op_sel_hi:[1,0,1]
	v_pk_fma_f32 v[72:73], v[238:239], s[90:91], v[72:73] op_sel_hi:[1,0,1]
	v_pk_fma_f32 v[74:75], v[240:241], s[90:91], v[74:75] op_sel_hi:[1,0,1]
	s_add_u32 s18, s10, 0x120000
	s_addc_u32 s19, s11, 0
	global_load_dwordx2 v[248:249], v252, s[12:13] offset:1152
	global_load_dwordx4 v[172:175], v247, s[18:19]
	global_load_dwordx4 v[176:179], v247, s[18:19] offset:16
	global_load_dwordx4 v[180:183], v247, s[18:19] offset:512
	global_load_dwordx4 v[238:241], v247, s[18:19] offset:528
	global_store_dwordx4 v247, v[126:129], s[14:15]
	global_store_dwordx4 v247, v[122:125], s[14:15] offset:16
	global_store_dwordx4 v247, v[110:113], s[14:15] offset:512
	global_store_dwordx4 v247, v[106:109], s[14:15] offset:528
	global_store_dwordx4 v247, v[118:121], s[44:45]
	global_store_dwordx4 v247, v[114:117], s[44:45] offset:16
	global_store_dwordx4 v247, v[102:105], s[44:45] offset:512
	global_store_dwordx4 v247, v[98:101], s[44:45] offset:528
	global_store_dwordx4 v247, v[92:95], s[46:47]
	global_store_dwordx4 v247, v[88:91], s[46:47] offset:16
	global_store_dwordx4 v247, v[80:83], s[46:47] offset:512
	global_store_dwordx4 v247, v[72:75], s[46:47] offset:528
	s_add_u32 s14, s10, 0x140000
	s_addc_u32 s15, s11, 0
	global_load_dwordx2 v[92:93], v252, s[12:13] offset:1280
	global_load_dwordx4 v[126:129], v247, s[14:15]
	global_load_dwordx4 v[122:125], v247, s[14:15] offset:16
	global_load_dwordx4 v[110:113], v247, s[14:15] offset:512
	global_load_dwordx4 v[106:109], v247, s[14:15] offset:528
	s_add_u32 s44, s10, 0x160000
	s_addc_u32 s45, s11, 0
	global_load_dwordx2 v[88:89], v252, s[12:13] offset:1408
	global_load_dwordx4 v[118:121], v247, s[44:45]
	global_load_dwordx4 v[114:117], v247, s[44:45] offset:16
	global_load_dwordx4 v[102:105], v247, s[44:45] offset:512
	global_load_dwordx4 v[98:101], v247, s[44:45] offset:528
	s_waitcnt vmcnt(32)
	v_pk_add_f32 v[130:131], v[130:131], v[184:185] op_sel_hi:[1,0]
	v_pk_add_f32 v[132:133], v[132:133], v[184:185] op_sel_hi:[1,0]
	v_pk_add_f32 v[134:135], v[134:135], v[184:185] op_sel_hi:[1,0]
	v_pk_add_f32 v[136:137], v[136:137], v[184:185] op_sel_hi:[1,0]
	v_pk_add_f32 v[138:139], v[138:139], v[184:185] op_sel_hi:[1,0]
	v_pk_add_f32 v[140:141], v[140:141], v[184:185] op_sel_hi:[1,0]
	v_pk_add_f32 v[142:143], v[142:143], v[184:185] op_sel_hi:[1,0]
	v_pk_add_f32 v[144:145], v[144:145], v[184:185] op_sel_hi:[1,0]
	v_pk_mul_f32 v[130:131], v[130:131], v[184:185] op_sel:[0,1] op_sel_hi:[1,1]
	v_pk_mul_f32 v[132:133], v[132:133], v[184:185] op_sel:[0,1] op_sel_hi:[1,1]
	v_pk_mul_f32 v[134:135], v[134:135], v[184:185] op_sel:[0,1] op_sel_hi:[1,1]
	v_pk_mul_f32 v[136:137], v[136:137], v[184:185] op_sel:[0,1] op_sel_hi:[1,1]
	v_pk_mul_f32 v[138:139], v[138:139], v[184:185] op_sel:[0,1] op_sel_hi:[1,1]
	v_pk_mul_f32 v[140:141], v[140:141], v[184:185] op_sel:[0,1] op_sel_hi:[1,1]
	v_pk_mul_f32 v[142:143], v[142:143], v[184:185] op_sel:[0,1] op_sel_hi:[1,1]
	v_pk_mul_f32 v[144:145], v[144:145], v[184:185] op_sel:[0,1] op_sel_hi:[1,1]
	v_pk_fma_f32 v[130:131], v[190:191], v[130:131], v[206:207]
	v_pk_fma_f32 v[132:133], v[192:193], v[132:133], v[208:209]
	v_pk_fma_f32 v[134:135], v[194:195], v[134:135], v[210:211]
	v_pk_fma_f32 v[136:137], v[196:197], v[136:137], v[212:213]
	v_pk_fma_f32 v[138:139], v[198:199], v[138:139], v[214:215]
	v_pk_fma_f32 v[140:141], v[200:201], v[140:141], v[216:217]
	v_pk_fma_f32 v[142:143], v[202:203], v[142:143], v[234:235]
	v_pk_fma_f32 v[144:145], v[204:205], v[144:145], v[236:237]
	v_pk_fma_f32 v[84:85], v[130:131], s[90:91], v[84:85] op_sel_hi:[1,0,1]
	v_pk_fma_f32 v[86:87], v[132:133], s[90:91], v[86:87] op_sel_hi:[1,0,1]
	v_pk_fma_f32 v[76:77], v[134:135], s[90:91], v[76:77] op_sel_hi:[1,0,1]
	v_pk_fma_f32 v[78:79], v[136:137], s[90:91], v[78:79] op_sel_hi:[1,0,1]
	v_pk_fma_f32 v[68:69], v[138:139], s[90:91], v[68:69] op_sel_hi:[1,0,1]
	v_pk_fma_f32 v[70:71], v[140:141], s[90:91], v[70:71] op_sel_hi:[1,0,1]
	v_pk_fma_f32 v[64:65], v[142:143], s[90:91], v[64:65] op_sel_hi:[1,0,1]
	v_pk_fma_f32 v[66:67], v[144:145], s[90:91], v[66:67] op_sel_hi:[1,0,1]
	global_store_dwordx4 v247, v[84:87], s[48:49]
	global_store_dwordx4 v247, v[76:79], s[48:49] offset:16
	global_store_dwordx4 v247, v[68:71], s[48:49] offset:512
	global_store_dwordx4 v247, v[64:67], s[48:49] offset:528
	s_waitcnt vmcnt(31)
;   __device__ __forceinline__ void emit(const EpiPre& q0, int row, int col, f32x4 a, f32x4 b, const f32x4 (&hb)[2][2], const float (&hs)[2][4], int ai_, int m_, int bj_) const {
;     ...
;     } else if (MODE == E_RES) {
;       const f32x4 r0 = q.a0, r1 = q.a1;
;       float* o = (float*)e.out + (size_t)row * DM + col;
;       *(f32x4*)o = (f32x4){ALPHA * r0[0] + v[0], ALPHA * r0[1] + v[1], ALPHA * r0[2] + v[2], ALPHA * r0[3] + v[3]};
;       *(f32x4*)(o + 4) = (f32x4){ALPHA * r1[0] + v[4], ALPHA * r1[1] + v[5], ALPHA * r1[2] + v[6], ALPHA * r1[3] + v[7]};
; __device__ __forceinline__ void ln_phase(const float* in, float* outf, bf16_t* outb, const float* g, const float* b, int wv0) {
;     ...
; #pragma unroll
;     for (int i = 0; i < 8; ++i) {
;       const f32x4 y = v[i] * rstd * gg[i] + bb[i];
	v_pk_add_f32 v[146:147], v[146:147], v[242:243] op_sel_hi:[1,0]
	v_pk_add_f32 v[148:149], v[148:149], v[242:243] op_sel_hi:[1,0]
	v_pk_add_f32 v[150:151], v[150:151], v[242:243] op_sel_hi:[1,0]
	v_pk_add_f32 v[152:153], v[152:153], v[242:243] op_sel_hi:[1,0]
	v_pk_add_f32 v[154:155], v[154:155], v[242:243] op_sel_hi:[1,0]
	v_pk_add_f32 v[156:157], v[156:157], v[242:243] op_sel_hi:[1,0]
	v_pk_add_f32 v[158:159], v[158:159], v[242:243] op_sel_hi:[1,0]
	v_pk_add_f32 v[160:161], v[160:161], v[242:243] op_sel_hi:[1,0]
	v_pk_mul_f32 v[146:147], v[146:147], v[242:243] op_sel:[0,1] op_sel_hi:[1,1]
	v_pk_mul_f32 v[148:149], v[148:149], v[242:243] op_sel:[0,1] op_sel_hi:[1,1]
	v_pk_mul_f32 v[150:151], v[150:151], v[242:243] op_sel:[0,1] op_sel_hi:[1,1]
	v_pk_mul_f32 v[152:153], v[152:153], v[242:243] op_sel:[0,1] op_sel_hi:[1,1]
	v_pk_mul_f32 v[154:155], v[154:155], v[242:243] op_sel:[0,1] op_sel_hi:[1,1]
	v_pk_mul_f32 v[156:157], v[156:157], v[242:243] op_sel:[0,1] op_sel_hi:[1,1]
	v_pk_mul_f32 v[158:159], v[158:159], v[242:243] op_sel:[0,1] op_sel_hi:[1,1]
	v_pk_mul_f32 v[160:161], v[160:161], v[242:243] op_sel:[0,1] op_sel_hi:[1,1]
	v_pk_fma_f32 v[146:147], v[190:191], v[146:147], v[206:207]
	v_pk_fma_f32 v[148:149], v[192:193], v[148:149], v[208:209]
	v_pk_fma_f32 v[150:151], v[194:195], v[150:151], v[210:211]
	v_pk_fma_f32 v[152:153], v[196:197], v[152:153], v[212:213]
	v_pk_fma_f32 v[154:155], v[198:199], v[154:155], v[214:215]
	v_pk_fma_f32 v[156:157], v[200:201], v[156:157], v[216:217]
	v_pk_fma_f32 v[158:159], v[202:203], v[158:159], v[234:235]
	v_pk_fma_f32 v[160:161], v[204:205], v[160:161], v[236:237]
	v_pk_fma_f32 v[60:61], v[146:147], s[90:91], v[60:61] op_sel_hi:[1,0,1]
	v_pk_fma_f32 v[62:63], v[148:149], s[90:91], v[62:63] op_sel_hi:[1,0,1]
	v_pk_fma_f32 v[56:57], v[150:151], s[90:91], v[56:57] op_sel_hi:[1,0,1]
	v_pk_fma_f32 v[58:59], v[152:153], s[90:91], v[58:59] op_sel_hi:[1,0,1]
	v_pk_fma_f32 v[52:53], v[154:155], s[90:91], v[52:53] op_sel_hi:[1,0,1]
	v_pk_fma_f32 v[54:55], v[156:157], s[90:91], v[54:55] op_sel_hi:[1,0,1]
	v_pk_fma_f32 v[44:45], v[158:159], s[90:91], v[44:45] op_sel_hi:[1,0,1]
	v_pk_fma_f32 v[46:47], v[160:161], s[90:91], v[46:47] op_sel_hi:[1,0,1]
	global_store_dwordx4 v247, v[60:63], s[16:17]
	global_store_dwordx4 v247, v[56:59], s[16:17] offset:16
	global_store_dwordx4 v247, v[52:55], s[16:17] offset:512
	global_store_dwordx4 v247, v[44:47], s[16:17] offset:528
	s_waitcnt vmcnt(30)
	v_pk_add_f32 v[172:173], v[172:173], v[248:249] op_sel_hi:[1,0]
	v_pk_add_f32 v[174:175], v[174:175], v[248:249] op_sel_hi:[1,0]
	v_pk_add_f32 v[176:177], v[176:177], v[248:249] op_sel_hi:[1,0]
	v_pk_add_f32 v[178:179], v[178:179], v[248:249] op_sel_hi:[1,0]
	v_pk_add_f32 v[180:181], v[180:181], v[248:249] op_sel_hi:[1,0]
	v_pk_add_f32 v[182:183], v[182:183], v[248:249] op_sel_hi:[1,0]
	v_pk_add_f32 v[238:239], v[238:239], v[248:249] op_sel_hi:[1,0]
	v_pk_add_f32 v[240:241], v[240:241], v[248:249] op_sel_hi:[1,0]
	v_pk_mul_f32 v[172:173], v[172:173], v[248:249] op_sel:[0,1] op_sel_hi:[1,1]
	v_pk_mul_f32 v[174:175], v[174:175], v[248:249] op_sel:[0,1] op_sel_hi:[1,1]
	v_pk_mul_f32 v[176:177], v[176:177], v[248:249] op_sel:[0,1] op_sel_hi:[1,1]
	v_pk_mul_f32 v[178:179], v[178:179], v[248:249] op_sel:[0,1] op_sel_hi:[1,1]
	v_pk_mul_f32 v[180:181], v[180:181], v[248:249] op_sel:[0,1] op_sel_hi:[1,1]
	v_pk_mul_f32 v[182:183], v[182:183], v[248:249] op_sel:[0,1] op_sel_hi:[1,1]
	v_pk_mul_f32 v[238:239], v[238:239], v[248:249] op_sel:[0,1] op_sel_hi:[1,1]
	v_pk_mul_f32 v[240:241], v[240:241], v[248:249] op_sel:[0,1] op_sel_hi:[1,1]
	v_pk_fma_f32 v[172:173], v[190:191], v[172:173], v[206:207]
	v_pk_fma_f32 v[174:175], v[192:193], v[174:175], v[208:209]
	v_pk_fma_f32 v[176:177], v[194:195], v[176:177], v[210:211]
	v_pk_fma_f32 v[178:179], v[196:197], v[178:179], v[212:213]
	v_pk_fma_f32 v[180:181], v[198:199], v[180:181], v[214:215]
	v_pk_fma_f32 v[182:183], v[200:201], v[182:183], v[216:217]
	v_pk_fma_f32 v[238:239], v[202:203], v[238:239], v[234:235]
	v_pk_fma_f32 v[240:241], v[204:205], v[240:241], v[236:237]
	v_pk_fma_f32 v[48:49], v[172:173], s[90:91], v[48:49] op_sel_hi:[1,0,1]
	v_pk_fma_f32 v[50:51], v[174:175], s[90:91], v[50:51] op_sel_hi:[1,0,1]
	v_pk_fma_f32 v[40:41], v[176:177], s[90:91], v[40:41] op_sel_hi:[1,0,1]
	v_pk_fma_f32 v[42:43], v[178:179], s[90:91], v[42:43] op_sel_hi:[1,0,1]
	v_pk_fma_f32 v[36:37], v[180:181], s[90:91], v[36:37] op_sel_hi:[1,0,1]
	v_pk_fma_f32 v[38:39], v[182:183], s[90:91], v[38:39] op_sel_hi:[1,0,1]
	v_pk_fma_f32 v[32:33], v[238:239], s[90:91], v[32:33] op_sel_hi:[1,0,1]
	v_pk_fma_f32 v[34:35], v[240:241], s[90:91], v[34:35] op_sel_hi:[1,0,1]
	global_store_dwordx4 v247, v[48:51], s[18:19]
	global_store_dwordx4 v247, v[40:43], s[18:19] offset:16
	global_store_dwordx4 v247, v[36:39], s[18:19] offset:512
	global_store_dwordx4 v247, v[32:35], s[18:19] offset:528
	s_waitcnt vmcnt(17)
;   __device__ __forceinline__ void emit(const EpiPre& q0, int row, int col, f32x4 a, f32x4 b, const f32x4 (&hb)[2][2], const float (&hs)[2][4], int ai_, int m_, int bj_) const {
;     ...
;     } else if (MODE == E_RES) {
;       const f32x4 r0 = q.a0, r1 = q.a1;
;       float* o = (float*)e.out + (size_t)row * DM + col;
;       *(f32x4*)o = (f32x4){ALPHA * r0[0] + v[0], ALPHA * r0[1] + v[1], ALPHA * r0[2] + v[2], ALPHA * r0[3] + v[3]};
;       *(f32x4*)(o + 4) = (f32x4){ALPHA * r1[0] + v[4], ALPHA * r1[1] + v[5], ALPHA * r1[2] + v[6], ALPHA * r1[3] + v[7]};
; __device__ __forceinline__ void ln_phase(const float* in, float* outf, bf16_t* outb, const float* g, const float* b, int wv0) {
;     ...
; #pragma unroll
;     for (int i = 0; i < 8; ++i) {
;       const f32x4 y = v[i] * rstd * gg[i] + bb[i];
	v_pk_add_f32 v[126:127], v[126:127], v[92:93] op_sel_hi:[1,0]
	v_pk_add_f32 v[128:129], v[128:129], v[92:93] op_sel_hi:[1,0]
	v_pk_add_f32 v[122:123], v[122:123], v[92:93] op_sel_hi:[1,0]
	v_pk_add_f32 v[124:125], v[124:125], v[92:93] op_sel_hi:[1,0]
	v_pk_add_f32 v[110:111], v[110:111], v[92:93] op_sel_hi:[1,0]
	v_pk_add_f32 v[112:113], v[112:113], v[92:93] op_sel_hi:[1,0]
	v_pk_add_f32 v[106:107], v[106:107], v[92:93] op_sel_hi:[1,0]
	v_pk_add_f32 v[108:109], v[108:109], v[92:93] op_sel_hi:[1,0]
	v_pk_mul_f32 v[126:127], v[126:127], v[92:93] op_sel:[0,1] op_sel_hi:[1,1]
	v_pk_mul_f32 v[128:129], v[128:129], v[92:93] op_sel:[0,1] op_sel_hi:[1,1]
	v_pk_mul_f32 v[122:123], v[122:123], v[92:93] op_sel:[0,1] op_sel_hi:[1,1]
	v_pk_mul_f32 v[124:125], v[124:125], v[92:93] op_sel:[0,1] op_sel_hi:[1,1]
	v_pk_mul_f32 v[110:111], v[110:111], v[92:93] op_sel:[0,1] op_sel_hi:[1,1]
	v_pk_mul_f32 v[112:113], v[112:113], v[92:93] op_sel:[0,1] op_sel_hi:[1,1]
	v_pk_mul_f32 v[106:107], v[106:107], v[92:93] op_sel:[0,1] op_sel_hi:[1,1]
	v_pk_mul_f32 v[108:109], v[108:109], v[92:93] op_sel:[0,1] op_sel_hi:[1,1]
	v_pk_fma_f32 v[126:127], v[190:191], v[126:127], v[206:207]
	v_pk_fma_f32 v[128:129], v[192:193], v[128:129], v[208:209]
	v_pk_fma_f32 v[122:123], v[194:195], v[122:123], v[210:211]
	v_pk_fma_f32 v[124:125], v[196:197], v[124:125], v[212:213]
	v_pk_fma_f32 v[110:111], v[198:199], v[110:111], v[214:215]
	v_pk_fma_f32 v[112:113], v[200:201], v[112:113], v[216:217]
	v_pk_fma_f32 v[106:107], v[202:203], v[106:107], v[234:235]
	v_pk_fma_f32 v[108:109], v[204:205], v[108:109], v[236:237]
	v_pk_fma_f32 v[28:29], v[126:127], s[90:91], v[28:29] op_sel_hi:[1,0,1]
	v_pk_fma_f32 v[30:31], v[128:129], s[90:91], v[30:31] op_sel_hi:[1,0,1]
	v_pk_fma_f32 v[24:25], v[122:123], s[90:91], v[24:25] op_sel_hi:[1,0,1]
	v_pk_fma_f32 v[26:27], v[124:125], s[90:91], v[26:27] op_sel_hi:[1,0,1]
	v_pk_fma_f32 v[20:21], v[110:111], s[90:91], v[20:21] op_sel_hi:[1,0,1]
	v_pk_fma_f32 v[22:23], v[112:113], s[90:91], v[22:23] op_sel_hi:[1,0,1]
	v_pk_fma_f32 v[12:13], v[106:107], s[90:91], v[12:13] op_sel_hi:[1,0,1]
	v_pk_fma_f32 v[14:15], v[108:109], s[90:91], v[14:15] op_sel_hi:[1,0,1]
	global_store_dwordx4 v247, v[28:31], s[14:15]
	global_store_dwordx4 v247, v[24:27], s[14:15] offset:16
	global_store_dwordx4 v247, v[20:23], s[14:15] offset:512
	global_store_dwordx4 v247, v[12:15], s[14:15] offset:528
	s_waitcnt vmcnt(16)
	v_pk_add_f32 v[118:119], v[118:119], v[88:89] op_sel_hi:[1,0]
	v_pk_add_f32 v[120:121], v[120:121], v[88:89] op_sel_hi:[1,0]
	v_pk_add_f32 v[114:115], v[114:115], v[88:89] op_sel_hi:[1,0]
	v_pk_add_f32 v[116:117], v[116:117], v[88:89] op_sel_hi:[1,0]
	v_pk_add_f32 v[102:103], v[102:103], v[88:89] op_sel_hi:[1,0]
	v_pk_add_f32 v[104:105], v[104:105], v[88:89] op_sel_hi:[1,0]
	v_pk_add_f32 v[98:99], v[98:99], v[88:89] op_sel_hi:[1,0]
	v_pk_add_f32 v[100:101], v[100:101], v[88:89] op_sel_hi:[1,0]
	v_pk_mul_f32 v[118:119], v[118:119], v[88:89] op_sel:[0,1] op_sel_hi:[1,1]
	v_pk_mul_f32 v[120:121], v[120:121], v[88:89] op_sel:[0,1] op_sel_hi:[1,1]
	v_pk_mul_f32 v[114:115], v[114:115], v[88:89] op_sel:[0,1] op_sel_hi:[1,1]
	v_pk_mul_f32 v[116:117], v[116:117], v[88:89] op_sel:[0,1] op_sel_hi:[1,1]
	v_pk_mul_f32 v[102:103], v[102:103], v[88:89] op_sel:[0,1] op_sel_hi:[1,1]
	v_pk_mul_f32 v[104:105], v[104:105], v[88:89] op_sel:[0,1] op_sel_hi:[1,1]
	v_pk_mul_f32 v[98:99], v[98:99], v[88:89] op_sel:[0,1] op_sel_hi:[1,1]
	v_pk_mul_f32 v[100:101], v[100:101], v[88:89] op_sel:[0,1] op_sel_hi:[1,1]
	v_pk_fma_f32 v[118:119], v[190:191], v[118:119], v[206:207]
	v_pk_fma_f32 v[120:121], v[192:193], v[120:121], v[208:209]
	v_pk_fma_f32 v[114:115], v[194:195], v[114:115], v[210:211]
	v_pk_fma_f32 v[116:117], v[196:197], v[116:117], v[212:213]
	v_pk_fma_f32 v[102:103], v[198:199], v[102:103], v[214:215]
	v_pk_fma_f32 v[104:105], v[200:201], v[104:105], v[216:217]
	v_pk_fma_f32 v[98:99], v[202:203], v[98:99], v[234:235]
	v_pk_fma_f32 v[100:101], v[204:205], v[100:101], v[236:237]
	v_pk_fma_f32 v[16:17], v[118:119], s[90:91], v[16:17] op_sel_hi:[1,0,1]
	v_pk_fma_f32 v[18:19], v[120:121], s[90:91], v[18:19] op_sel_hi:[1,0,1]
	v_pk_fma_f32 v[8:9], v[114:115], s[90:91], v[8:9] op_sel_hi:[1,0,1]
	v_pk_fma_f32 v[10:11], v[116:117], s[90:91], v[10:11] op_sel_hi:[1,0,1]
	v_pk_fma_f32 v[4:5], v[102:103], s[90:91], v[4:5] op_sel_hi:[1,0,1]
	v_pk_fma_f32 v[6:7], v[104:105], s[90:91], v[6:7] op_sel_hi:[1,0,1]
	v_pk_fma_f32 v[0:1], v[98:99], s[90:91], v[0:1] op_sel_hi:[1,0,1]
	v_pk_fma_f32 v[2:3], v[100:101], s[90:91], v[2:3] op_sel_hi:[1,0,1]
	global_store_dwordx4 v247, v[16:19], s[44:45]
	global_store_dwordx4 v247, v[8:11], s[44:45] offset:16
	global_store_dwordx4 v247, v[4:7], s[44:45] offset:512
	global_store_dwordx4 v247, v[0:3], s[44:45] offset:528
	s_mov_b64 s[0:1], 0x100000
	s_mov_b32 s42, s40
	s_mov_b64 s[14:15], s[6:7]
	s_mov_b64 s[12:13], s[4:5]
	s_and_b64 vcc, exec, s[2:3]
	s_mov_b32 s1, s41
	s_cbranch_vccz .LBB0_1418
	s_waitcnt vmcnt(0)
	s_cmpk_gt_u32 s23, 0xff
	s_cbranch_scc1 .LBB0_1433
	s_barrier

; __global__ void __launch_bounds__(512, 2) mega(Params p_unused) {
;   KP p = (KP)__builtin_amdgcn_kernarg_segment_ptr();
;   int wv0 = __builtin_amdgcn_readfirstlane((int)threadIdx.x >> 6);
;   extern __shared__ __attribute__((aligned(16))) unsigned char shm[];
	.amdhsa_kernel _Z4mega6Params
		.amdhsa_group_segment_fixed_size 0
		.amdhsa_private_segment_fixed_size 0
		.amdhsa_kernarg_size 472
		.amdhsa_user_sgpr_count 2
		.amdhsa_user_sgpr_dispatch_ptr 0
		.amdhsa_user_sgpr_queue_ptr 0
		.amdhsa_user_sgpr_kernarg_segment_ptr 1
		.amdhsa_user_sgpr_dispatch_id 0
		.amdhsa_user_sgpr_kernarg_preload_length 0
		.amdhsa_user_sgpr_kernarg_preload_offset 0
		.amdhsa_user_sgpr_private_segment_size 0
		.amdhsa_uses_dynamic_stack 0
		.amdhsa_enable_private_segment 0
		.amdhsa_system_sgpr_workgroup_id_x 1
		.amdhsa_system_sgpr_workgroup_id_y 0
		.amdhsa_system_sgpr_workgroup_id_z 0
		.amdhsa_system_sgpr_workgroup_info 0
		.amdhsa_system_vgpr_workitem_id 2
		.amdhsa_next_free_vgpr 256
		.amdhsa_next_free_sgpr 102
		.amdhsa_accum_offset 256
		.amdhsa_reserve_vcc 1
		.amdhsa_float_round_mode_32 0
		.amdhsa_float_round_mode_16_64 0
		.amdhsa_float_denorm_mode_32 3
		.amdhsa_float_denorm_mode_16_64 3
		.amdhsa_dx10_clamp 1
		.amdhsa_ieee_mode 1
		.amdhsa_fp16_overflow 0
		.amdhsa_tg_split 0
		.amdhsa_exception_fp_ieee_invalid_op 0
		.amdhsa_exception_fp_denorm_src 0
		.amdhsa_exception_fp_ieee_div_zero 0
		.amdhsa_exception_fp_ieee_overflow 0
		.amdhsa_exception_fp_ieee_underflow 0
		.amdhsa_exception_fp_ieee_inexact 0
		.amdhsa_exception_int_div_zero 0
	.end_amdhsa_kernel

; __global__ void __launch_bounds__(512, 2) mega(Params p_unused) {
;   KP p = (KP)__builtin_amdgcn_kernarg_segment_ptr();
;   int wv0 = __builtin_amdgcn_readfirstlane((int)threadIdx.x >> 6);
;   extern __shared__ __attribute__((aligned(16))) unsigned char shm[];
amdhsa.kernels:
  - .agpr_count:     0
    .args:
      - .offset:         0
        .size:           216
        .value_kind:     by_value
      - .offset:         216
        .size:           4
        .value_kind:     hidden_block_count_x
      - .offset:         220
        .size:           4
        .value_kind:     hidden_block_count_y
      - .offset:         224
        .size:           4
        .value_kind:     hidden_block_count_z
      - .offset:         228
        .size:           2
        .value_kind:     hidden_group_size_x
      - .offset:         230
        .size:           2
        .value_kind:     hidden_group_size_y
      - .offset:         232
        .size:           2
        .value_kind:     hidden_group_size_z
      - .offset:         234
        .size:           2
        .value_kind:     hidden_remainder_x
      - .offset:         236
        .size:           2
        .value_kind:     hidden_remainder_y
      - .offset:         238
        .size:           2
        .value_kind:     hidden_remainder_z
      - .offset:         256
        .size:           8
        .value_kind:     hidden_global_offset_x
      - .offset:         264
        .size:           8
        .value_kind:     hidden_global_offset_y
      - .offset:         272
        .size:           8
        .value_kind:     hidden_global_offset_z
      - .offset:         280
        .size:           2
        .value_kind:     hidden_grid_dims
      - .offset:         304
        .size:           8
        .value_kind:     hidden_multigrid_sync_arg
      - .offset:         336
        .size:           4
        .value_kind:     hidden_dynamic_lds_size
    .group_segment_fixed_size: 0
    .kernarg_segment_align: 8
    .kernarg_segment_size: 472
    .language:       OpenCL C
    .language_version:
      - 2
      - 0
    .max_flat_workgroup_size: 512
    .name:           _Z4mega6Params
    .private_segment_fixed_size: 0
    .sgpr_count:     108
    .sgpr_spill_count: 13
    .symbol:         _Z4mega6Params.kd
    .uniform_work_group_size: 1
    .uses_dynamic_stack: false
    .vgpr_count:     256
    .vgpr_spill_count: 0
    .wavefront_size: 64
